# adds: P14 split-K rows batched; win_attn_prompt Q fragments loaded one group ahead
# baseline (speedup 1.0000x reference)
; #define LAS __attribute__((address_space(3)))
; #define MFMA16(a, b, c) __builtin_amdgcn_mfma_f32_16x16x32_bf16((a), (b), (c), 0, 0, 0)
; template <int D, int NKT, bool WIN> ...
;     ...
; #pragma unroll
;     for (int kt = 0; kt < NKT; ++kt) { s[kt] = (f32x4){0.f, 0.f, 0.f, 0.f};
; #pragma unroll
;         for (int ks = 0; ks < D / 32; ++ks) { const bf16x8 a = *(const LAS bf16x8*)(Kl + (kt * 16 + fr) * kstr + (ks * 32 + fq * 8) * 2); s[kt] = MFMA16(a, qf[ks], s[kt]); }
;         if ((kt & (D == 64 ? 3 : 1)) == (D == 64 ? 3 : 1)) __builtin_amdgcn_sched_barrier(0); }
; __device__ __forceinline__ void win_attn_prompt_unit(int unit, const bf16* Z, bf16* HB, const float* sinks, LAS unsigned char* lds, int tid, int wave, int lane) {
;     ...
;     const int g = wave >> 1, hq = kvh * 4 + g; const float slope = exp2f(-0.5f * (float)(hq + 1)), sink = sinks[hq];
; #pragma unroll 1
;     for (int i = 0; i < 4; ++i) { const int tl = ((wave & 1) * 4 + i) * 16 + fr; const size_t row = (size_t)b * SEQ + n * 128 + tl;
;         bf16x8 qf[2];
; #pragma unroll
;         for (int ks = 0; ks < 2; ++ks) qf[ks] = __builtin_bit_cast(bf16x8, ld8_bf16(Z + row * NIN + ZQA + hq * 64 + ks * 32 + fq * 8));
;         f32x4 o[4];
;         attn_group<64, 16, true>(Kl, KSTR, Vl, VSTR, qf, n * 128 + tl, pos0, slope, sink, 0.125f, fr, fq, o);
.LBB0_599:
	s_or_b64 exec, exec, s[10:11]
	s_and_b32 s0, s2, 3
	s_lshl_b32 s0, s0, 8
	s_add_i32 s0, s72, s0
	s_lshl_b64 s[46:47], s[0:1], 1
	s_lshl_b32 s0, s5, 2
	s_add_i32 s0, s0, s3
	s_add_i32 s5, s0, 1
	v_cvt_f32_u32_e32 v2, s5
	s_mov_b32 s5, 0xc2fc0000
	s_and_b32 s44, s74, 0xf80
	v_readlane_b32 s16, v254, 29
	v_mul_f32_e32 v3, -0.5, v2
	v_cmp_gt_f32_e32 vcc, s5, v3
	s_and_b64 s[8:9], vcc, exec
	s_cselect_b32 s5, 0xffffffc0, 0
	s_lshl_b32 s0, s0, 2
	v_mov_b32_e32 v4, s0
	v_readlane_b32 s17, v254, 30
	s_waitcnt lgkmcnt(0)
	s_barrier
	v_cndmask_b32_e32 v3, 0, v104, vcc
	v_fmac_f32_e32 v3, -0.5, v2
	s_nop 0
	global_load_dword v107, v4, s[16:17]
	v_exp_f32_e32 v2, v3
	v_mov_b64_e32 v[6:7], s[46:47]
	v_readlane_b32 s18, v254, 31
	v_readlane_b32 s20, v254, 33
	v_ldexp_f32 v83, v2, s5
	s_ashr_i32 s5, s4, 31
	s_lshl_b64 s[48:49], s[4:5], 12
	v_or_b32_e32 v2, s48, v74
	v_or_b32_e32 v2, s44, v2
	v_mov_b32_e32 v3, s49
	v_readlane_b32 s22, v254, 35
	v_readlane_b32 s24, v254, 37
	v_readlane_b32 s26, v254, 39
	v_readlane_b32 s28, v254, 41
	v_readlane_b32 s30, v254, 43
	v_lshlrev_b64 v[4:5], 12, v[2:3]
	v_mad_u64_u32 v[2:3], s[50:51], v2, s73, v[6:7]
	v_readlane_b32 s19, v254, 32
	v_readlane_b32 s21, v254, 34
	v_readlane_b32 s23, v254, 36
	v_readlane_b32 s25, v254, 38
	v_readlane_b32 s27, v254, 40
	v_readlane_b32 s29, v254, 42
	v_readlane_b32 s31, v254, 44
	v_or_b32_e32 v8, s13, v72
	s_cmp_lg_u32 s12, 0
	s_movk_i32 s14, 0xffef
	s_movk_i32 s16, 0xffee
	s_movk_i32 s18, 0xffed
	s_movk_i32 s20, 0xffec
	s_movk_i32 s22, 0xffdf
	s_movk_i32 s24, 0xffde
	s_movk_i32 s26, 0xffdd
	s_movk_i32 s28, 0xffdc
	s_movk_i32 s30, 0xffcf
	s_movk_i32 s34, 0xffce
	s_movk_i32 s36, 0xffcd
	s_movk_i32 s38, 0xffcc
	s_movk_i32 s40, 0xffbf
	s_movk_i32 s42, 0xffbe
	s_movk_i32 s44, 0xffbd
	v_lshl_add_u64 v[4:5], v[4:5], 0, s[46:47]
	s_movk_i32 s46, 0xffbc
	v_mad_i32_i24 v3, s49, v105, v3
	s_movk_i32 s48, 0xffaf
	s_movk_i32 s50, 0xffae
	s_movk_i32 s52, 0xffad
	s_movk_i32 s54, 0xffac
	s_movk_i32 s56, 0xff9f
	s_movk_i32 s58, 0xff9e
	s_movk_i32 s60, 0xff9d
	s_movk_i32 s62, 0xff9c
	s_movk_i32 s64, 0xff8f
	s_movk_i32 s66, 0xff8e
	s_movk_i32 s68, 0xff8d
	s_movk_i32 s70, 0xff8c
	s_mov_b32 s0, 0
	s_cselect_b64 s[4:5], -1, 0
	v_cmp_lt_i32_e64 s[8:9], -2, v8
	v_cmp_lt_i32_e64 s[10:11], -3, v8
	v_cmp_lt_i32_e64 s[12:13], -4, v8
	v_cmp_lt_i32_e64 s[14:15], s14, v8
	v_cmp_lt_i32_e64 s[16:17], s16, v8
	v_cmp_lt_i32_e64 s[18:19], s18, v8
	v_cmp_lt_i32_e64 s[20:21], s20, v8
	v_cmp_lt_i32_e64 s[22:23], s22, v8
	v_cmp_lt_i32_e64 s[24:25], s24, v8
	v_cmp_lt_i32_e64 s[26:27], s26, v8
	v_cmp_lt_i32_e64 s[28:29], s28, v8
	v_cmp_lt_i32_e64 s[30:31], s30, v8
	v_cmp_lt_i32_e64 s[34:35], s34, v8
	v_cmp_lt_i32_e64 s[36:37], s36, v8
	v_cmp_lt_i32_e64 s[38:39], s38, v8
	v_cmp_lt_i32_e64 s[40:41], s40, v8
	v_cmp_lt_i32_e64 s[42:43], s42, v8
	v_cmp_lt_i32_e64 s[44:45], s44, v8
	v_cmp_lt_i32_e64 s[46:47], s46, v8
	v_cmp_lt_i32_e64 s[48:49], s48, v8
	v_lshl_add_u64 v[84:85], v[76:77], 0, v[4:5]
	v_lshl_add_u64 v[86:87], v[78:79], 0, v[2:3]
	v_cmp_lt_i32_e64 s[50:51], s50, v8
	v_cmp_lt_i32_e64 s[52:53], s52, v8
	v_cmp_lt_i32_e64 s[54:55], s54, v8
	v_cmp_lt_i32_e64 s[56:57], s56, v8
	v_cmp_lt_i32_e64 s[58:59], s58, v8
	v_cmp_lt_i32_e64 s[60:61], s60, v8
	v_cmp_lt_i32_e64 s[62:63], s62, v8
	v_cmp_lt_i32_e64 s[64:65], s64, v8
	v_cmp_lt_i32_e64 s[66:67], s66, v8
	v_cmp_lt_i32_e64 s[68:69], s68, v8
	v_cmp_lt_i32_e64 s[70:71], s70, v8
	global_load_dwordx4 v[232:235], v[86:87], off offset:-64
	global_load_dwordx4 v[236:239], v[86:87], off
.LBB0_600:
	s_waitcnt vmcnt(0)
	v_mov_b64_e32 v[2:3], v[232:233]
	v_mov_b64_e32 v[4:5], v[234:235]
	v_mov_b64_e32 v[108:109], v[236:237]
	v_mov_b64_e32 v[110:111], v[238:239]
	s_mov_b64 s[96:97], 0x2c000
	v_lshl_add_u64 v[240:241], v[86:87], 0, s[96:97]
	global_load_dwordx4 v[232:235], v[240:241], off offset:-64
	global_load_dwordx4 v[236:239], v[240:241], off
	ds_read_b128 v[6:9], v99
	ds_read_b128 v[10:13], v99 offset:64
	s_waitcnt lgkmcnt(1)
	v_mfma_f32_16x16x32_bf16 v[6:9], v[6:9], v[2:5], 0
	s_waitcnt lgkmcnt(0)
	v_mfma_f32_16x16x32_bf16 v[62:65], v[10:13], v[108:111], v[6:9]
	ds_read_b128 v[10:13], v99 offset:2368
	s_nop 4
	ds_read_b128 v[6:9], v99 offset:2304
	s_waitcnt lgkmcnt(0)
	v_mfma_f32_16x16x32_bf16 v[6:9], v[6:9], v[2:5], 0
	v_mfma_f32_16x16x32_bf16 v[58:61], v[10:13], v[108:111], v[6:9]
	ds_read_b128 v[10:13], v99 offset:4672
	s_nop 5
	ds_read_b128 v[6:9], v99 offset:4608
	s_waitcnt lgkmcnt(0)
	v_mfma_f32_16x16x32_bf16 v[6:9], v[6:9], v[2:5], 0
	v_mfma_f32_16x16x32_bf16 v[54:57], v[10:13], v[108:111], v[6:9]
	ds_read_b128 v[10:13], v100 offset:64
	s_nop 5
	ds_read_b128 v[6:9], v100
	s_waitcnt lgkmcnt(0)
	v_mfma_f32_16x16x32_bf16 v[6:9], v[6:9], v[2:5], 0
	v_mfma_f32_16x16x32_bf16 v[50:53], v[10:13], v[108:111], v[6:9]
	s_nop 6
	ds_read_b128 v[6:9], v99 offset:9216
	ds_read_b128 v[10:13], v99 offset:9280
	ds_read_b128 v[14:17], v99 offset:11520
	ds_read_b128 v[18:21], v99 offset:11584
	s_waitcnt lgkmcnt(3)
	v_mfma_f32_16x16x32_bf16 v[6:9], v[6:9], v[2:5], 0
	s_waitcnt lgkmcnt(2)
	v_mfma_f32_16x16x32_bf16 v[46:49], v[10:13], v[108:111], v[6:9]
	ds_read_b128 v[10:13], v99 offset:13888
	s_nop 4
	ds_read_b128 v[6:9], v99 offset:13824
	s_waitcnt lgkmcnt(3)
	v_mfma_f32_16x16x32_bf16 v[14:17], v[14:17], v[2:5], 0
	s_waitcnt lgkmcnt(2)
	v_mfma_f32_16x16x32_bf16 v[42:45], v[18:21], v[108:111], v[14:17]
	s_waitcnt lgkmcnt(0)
	v_mfma_f32_16x16x32_bf16 v[6:9], v[6:9], v[2:5], 0
	s_nop 3
	ds_read_b128 v[14:17], v99 offset:16128
	v_mfma_f32_16x16x32_bf16 v[38:41], v[10:13], v[108:111], v[6:9]
	s_nop 2
	ds_read_b128 v[6:9], v99 offset:16192
	s_waitcnt lgkmcnt(1)
; #define LAS __attribute__((address_space(3)))
; #define MFMA16(a, b, c) __builtin_amdgcn_mfma_f32_16x16x32_bf16((a), (b), (c), 0, 0, 0)
; template <int D, int NKT, bool WIN> ...
;     ...
; #pragma unroll
;     for (int kt = 0; kt < NKT; ++kt) { s[kt] = (f32x4){0.f, 0.f, 0.f, 0.f};
; #pragma unroll
;         for (int ks = 0; ks < D / 32; ++ks) { const bf16x8 a = *(const LAS bf16x8*)(Kl + (kt * 16 + fr) * kstr + (ks * 32 + fq * 8) * 2); s[kt] = MFMA16(a, qf[ks], s[kt]); }
;         if ((kt & (D == 64 ? 3 : 1)) == (D == 64 ? 3 : 1)) __builtin_amdgcn_sched_barrier(0); }
;     float m = -1e30f;
; #pragma unroll
;     for (int kt = 0; kt < NKT; ++kt)
; #pragma unroll
;         for (int j = 0; j < 4; ++j) { float v = s[kt][j] * scale;
;             if (WIN) { const int kpos = kbase + kt * 16 + fq * 4 + j, dist = qpos - kpos; const bool valid = (kpos >= 0) && (dist >= 0) && (dist < 128); v = valid ? v - slope * (float)dist : -1e30f; }
;             s[kt][j] = v; m = fmaxf(m, v); }
	v_mfma_f32_16x16x32_bf16 v[10:13], v[14:17], v[2:5], 0
	s_waitcnt lgkmcnt(0)
	v_mfma_f32_16x16x32_bf16 v[34:37], v[6:9], v[108:111], v[10:13]
	ds_read_b128 v[6:9], v99 offset:18432
	s_nop 4
	ds_read_b128 v[10:13], v99 offset:18496
	ds_read_b128 v[14:17], v99 offset:20736
	ds_read_b128 v[18:21], v99 offset:20800
	s_waitcnt lgkmcnt(3)
	v_mfma_f32_16x16x32_bf16 v[6:9], v[6:9], v[2:5], 0
	s_waitcnt lgkmcnt(2)
	v_mfma_f32_16x16x32_bf16 v[30:33], v[10:13], v[108:111], v[6:9]
	ds_read_b128 v[10:13], v99 offset:23104
	s_nop 4
	ds_read_b128 v[6:9], v99 offset:23040
	s_waitcnt lgkmcnt(3)
	v_mfma_f32_16x16x32_bf16 v[14:17], v[14:17], v[2:5], 0
	s_waitcnt lgkmcnt(2)
	v_mfma_f32_16x16x32_bf16 v[26:29], v[18:21], v[108:111], v[14:17]
	s_waitcnt lgkmcnt(0)
	v_mfma_f32_16x16x32_bf16 v[6:9], v[6:9], v[2:5], 0
	s_nop 3
	ds_read_b128 v[14:17], v99 offset:25344
	v_mfma_f32_16x16x32_bf16 v[22:25], v[10:13], v[108:111], v[6:9]
	s_nop 2
	ds_read_b128 v[6:9], v99 offset:25408
	s_waitcnt lgkmcnt(1)
	v_mfma_f32_16x16x32_bf16 v[10:13], v[14:17], v[2:5], 0
	s_waitcnt lgkmcnt(0)
	v_mfma_f32_16x16x32_bf16 v[18:21], v[6:9], v[108:111], v[10:13]
	ds_read_b128 v[6:9], v99 offset:27648
	s_nop 4
	ds_read_b128 v[10:13], v99 offset:27712
	s_waitcnt lgkmcnt(1)
	v_mfma_f32_16x16x32_bf16 v[6:9], v[6:9], v[2:5], 0
	ds_read_b128 v[112:115], v99 offset:32320
	s_waitcnt lgkmcnt(1)
	v_mfma_f32_16x16x32_bf16 v[14:17], v[10:13], v[108:111], v[6:9]
	ds_read_b128 v[10:13], v99 offset:30016
	s_nop 3
	ds_read_b128 v[6:9], v99 offset:29952
	s_waitcnt lgkmcnt(0)
	v_mfma_f32_16x16x32_bf16 v[6:9], v[6:9], v[2:5], 0
	v_mfma_f32_16x16x32_bf16 v[10:13], v[10:13], v[108:111], v[6:9]
	s_nop 6
	ds_read_b128 v[6:9], v99 offset:32256
	s_waitcnt lgkmcnt(0)
	v_mfma_f32_16x16x32_bf16 v[6:9], v[6:9], v[2:5], 0
	v_mfma_f32_16x16x32_bf16 v[6:9], v[112:115], v[108:111], v[6:9]
	ds_read_b128 v[112:115], v99 offset:34560
	s_waitcnt lgkmcnt(0)
	v_mfma_f32_16x16x32_bf16 v[2:5], v[112:115], v[2:5], 0
	ds_read_b128 v[112:115], v99 offset:34624
	s_waitcnt lgkmcnt(0)
	v_mfma_f32_16x16x32_bf16 v[2:5], v[112:115], v[108:111], v[2:5]
	v_add_u32_e32 v108, s0, v101
	v_add_co_u32_e32 v81, vcc, s33, v108
	v_cvt_f32_i32_e32 v81, v81
	v_mov_b32_e32 v82, v62
	s_and_b64 vcc, s[4:5], vcc
	s_mov_b32 s77, 0xf149f2ca
	v_pk_mul_f32 v[110:111], v[82:83], v[80:81]
	v_add_u32_e32 v81, 0x7f, v108
	v_sub_f32_e32 v62, v110, v111
	v_cndmask_b32_e32 v62, v106, v62, vcc
	v_cmp_gt_u32_e32 vcc, s33, v81
	v_cvt_f32_i32_e32 v81, v81
	v_mov_b32_e32 v82, v63
	s_and_b64 vcc, s[8:9], vcc
	v_pk_mul_f32 v[110:111], v[82:83], v[80:81]
	s_nop 0
	v_sub_f32_e32 v63, v110, v111
	v_add_u32_e32 v81, 0x7e, v108
	v_cndmask_b32_e32 v63, v106, v63, vcc
	v_cmp_gt_u32_e32 vcc, s33, v81
	v_cvt_f32_i32_e32 v81, v81
	v_mov_b32_e32 v82, v64
	s_and_b64 vcc, s[10:11], vcc
	v_max3_f32 v109, v62, s77, v63
	v_pk_mul_f32 v[110:111], v[82:83], v[80:81]
	v_add_u32_e32 v81, 0x7d, v108
	v_sub_f32_e32 v64, v110, v111
	v_cndmask_b32_e32 v64, v106, v64, vcc
	v_cmp_gt_u32_e32 vcc, s33, v81
	v_cvt_f32_i32_e32 v81, v81
	v_mov_b32_e32 v82, v65
	s_and_b64 vcc, s[12:13], vcc
	v_pk_mul_f32 v[110:111], v[82:83], v[80:81]
	s_nop 0
	v_sub_f32_e32 v65, v110, v111
	v_add_u32_e32 v81, 0x70, v108
	v_cndmask_b32_e32 v65, v106, v65, vcc
	v_cmp_gt_u32_e32 vcc, s33, v81
	v_cvt_f32_i32_e32 v81, v81
	v_mov_b32_e32 v82, v58
	s_and_b64 vcc, s[14:15], vcc
	v_max3_f32 v109, v109, v64, v65
	v_pk_mul_f32 v[110:111], v[82:83], v[80:81]
	v_add_u32_e32 v81, 0x6f, v108
	v_sub_f32_e32 v58, v110, v111
	v_cndmask_b32_e32 v58, v106, v58, vcc
	v_cmp_gt_u32_e32 vcc, s33, v81
	v_cvt_f32_i32_e32 v81, v81
	v_mov_b32_e32 v82, v59
	s_and_b64 vcc, s[16:17], vcc
	v_pk_mul_f32 v[110:111], v[82:83], v[80:81]
	s_nop 0
	v_sub_f32_e32 v59, v110, v111
	v_add_u32_e32 v81, 0x6e, v108
	v_cndmask_b32_e32 v59, v106, v59, vcc
	v_cmp_gt_u32_e32 vcc, s33, v81
	v_cvt_f32_i32_e32 v81, v81
	v_mov_b32_e32 v82, v60
	s_and_b64 vcc, s[18:19], vcc
	v_max3_f32 v109, v109, v58, v59
	v_pk_mul_f32 v[110:111], v[82:83], v[80:81]
	v_add_u32_e32 v81, 0x6d, v108
	v_sub_f32_e32 v60, v110, v111
	v_cndmask_b32_e32 v60, v106, v60, vcc
	v_cmp_gt_u32_e32 vcc, s33, v81
	v_cvt_f32_i32_e32 v81, v81
	v_mov_b32_e32 v82, v61
	s_and_b64 vcc, s[20:21], vcc
	v_pk_mul_f32 v[110:111], v[82:83], v[80:81]
	s_nop 0
	v_sub_f32_e32 v61, v110, v111
	v_add_u32_e32 v81, 0x60, v108
	v_cndmask_b32_e32 v61, v106, v61, vcc
	v_cmp_gt_u32_e32 vcc, s33, v81
	v_cvt_f32_i32_e32 v81, v81
	v_mov_b32_e32 v82, v54
	s_and_b64 vcc, s[22:23], vcc
	v_max3_f32 v109, v109, v60, v61
	v_pk_mul_f32 v[110:111], v[82:83], v[80:81]
	v_add_u32_e32 v81, 0x5f, v108
	v_sub_f32_e32 v54, v110, v111
	v_cndmask_b32_e32 v54, v106, v54, vcc
	v_cmp_gt_u32_e32 vcc, s33, v81
	v_cvt_f32_i32_e32 v81, v81
	v_mov_b32_e32 v82, v55
	s_and_b64 vcc, s[24:25], vcc
	v_pk_mul_f32 v[110:111], v[82:83], v[80:81]
	s_nop 0
	v_sub_f32_e32 v55, v110, v111
	v_add_u32_e32 v81, 0x5e, v108
	v_cndmask_b32_e32 v55, v106, v55, vcc
	v_cmp_gt_u32_e32 vcc, s33, v81
	v_cvt_f32_i32_e32 v81, v81
	v_mov_b32_e32 v82, v56
	s_and_b64 vcc, s[26:27], vcc
	v_max3_f32 v109, v109, v54, v55
	v_pk_mul_f32 v[110:111], v[82:83], v[80:81]
	v_add_u32_e32 v81, 0x5d, v108
	v_sub_f32_e32 v56, v110, v111
	v_cndmask_b32_e32 v56, v106, v56, vcc
	v_cmp_gt_u32_e32 vcc, s33, v81
	v_cvt_f32_i32_e32 v81, v81
	v_mov_b32_e32 v82, v57
	s_and_b64 vcc, s[28:29], vcc
	v_pk_mul_f32 v[110:111], v[82:83], v[80:81]
	s_nop 0
	v_sub_f32_e32 v57, v110, v111
	v_add_u32_e32 v81, 0x50, v108
	v_cndmask_b32_e32 v57, v106, v57, vcc
	v_cmp_gt_u32_e32 vcc, s33, v81
	v_cvt_f32_i32_e32 v81, v81
	v_mov_b32_e32 v82, v50
	s_and_b64 vcc, s[30:31], vcc
	v_max3_f32 v109, v109, v56, v57
; template <int D, int NKT, bool WIN> ...
;     ...
;         for (int j = 0; j < 4; ++j) { float v = s[kt][j] * scale;
;             if (WIN) { const int kpos = kbase + kt * 16 + fq * 4 + j, dist = qpos - kpos; const bool valid = (kpos >= 0) && (dist >= 0) && (dist < 128); v = valid ? v - slope * (float)dist : -1e30f; }
;             s[kt][j] = v; m = fmaxf(m, v); }
	v_pk_mul_f32 v[110:111], v[82:83], v[80:81]
	v_add_u32_e32 v81, 0x4f, v108
	v_sub_f32_e32 v50, v110, v111
	v_cndmask_b32_e32 v50, v106, v50, vcc
	v_cmp_gt_u32_e32 vcc, s33, v81
	v_cvt_f32_i32_e32 v81, v81
	v_mov_b32_e32 v82, v51
	s_and_b64 vcc, s[34:35], vcc
	v_pk_mul_f32 v[110:111], v[82:83], v[80:81]
	s_nop 0
	v_sub_f32_e32 v51, v110, v111
	v_add_u32_e32 v81, 0x4e, v108
	v_cndmask_b32_e32 v51, v106, v51, vcc
	v_cmp_gt_u32_e32 vcc, s33, v81
	v_cvt_f32_i32_e32 v81, v81
	v_mov_b32_e32 v82, v52
	s_and_b64 vcc, s[36:37], vcc
	v_max3_f32 v109, v109, v50, v51
	v_pk_mul_f32 v[110:111], v[82:83], v[80:81]
	v_add_u32_e32 v81, 0x4d, v108
	v_sub_f32_e32 v52, v110, v111
	v_cndmask_b32_e32 v52, v106, v52, vcc
	v_cmp_gt_u32_e32 vcc, s33, v81
	v_cvt_f32_i32_e32 v81, v81
	v_mov_b32_e32 v82, v53
	s_and_b64 vcc, s[38:39], vcc
	v_pk_mul_f32 v[110:111], v[82:83], v[80:81]
	s_nop 0
	v_sub_f32_e32 v53, v110, v111
	v_add_u32_e32 v81, 64, v108
	v_cndmask_b32_e32 v53, v106, v53, vcc
	v_cmp_gt_u32_e32 vcc, s33, v81
	v_cvt_f32_i32_e32 v81, v81
	v_mov_b32_e32 v82, v46
	s_and_b64 vcc, s[40:41], vcc
	v_max3_f32 v109, v109, v52, v53
	v_pk_mul_f32 v[110:111], v[82:83], v[80:81]
	v_add_u32_e32 v81, 63, v108
	v_sub_f32_e32 v46, v110, v111
	v_cndmask_b32_e32 v46, v106, v46, vcc
	v_cmp_gt_u32_e32 vcc, s33, v81
	v_cvt_f32_i32_e32 v81, v81
	v_mov_b32_e32 v82, v47
	s_and_b64 vcc, s[42:43], vcc
	v_pk_mul_f32 v[110:111], v[82:83], v[80:81]
	s_nop 0
	v_sub_f32_e32 v47, v110, v111
	v_add_u32_e32 v81, 62, v108
	v_cndmask_b32_e32 v47, v106, v47, vcc
	v_cmp_gt_u32_e32 vcc, s33, v81
	v_cvt_f32_i32_e32 v81, v81
	v_mov_b32_e32 v82, v48
	s_and_b64 vcc, s[44:45], vcc
	v_max3_f32 v109, v109, v46, v47
	v_pk_mul_f32 v[110:111], v[82:83], v[80:81]
	v_add_u32_e32 v81, 61, v108
	v_sub_f32_e32 v48, v110, v111
	v_cndmask_b32_e32 v48, v106, v48, vcc
	v_cmp_gt_u32_e32 vcc, s33, v81
	v_cvt_f32_i32_e32 v81, v81
	v_mov_b32_e32 v82, v49
	s_and_b64 vcc, s[46:47], vcc
	v_pk_mul_f32 v[110:111], v[82:83], v[80:81]
	s_nop 0
	v_sub_f32_e32 v49, v110, v111
	v_add_u32_e32 v81, 48, v108
	v_cndmask_b32_e32 v49, v106, v49, vcc
	v_cmp_gt_u32_e32 vcc, s33, v81
	v_cvt_f32_i32_e32 v81, v81
	v_mov_b32_e32 v82, v42
	s_and_b64 vcc, s[48:49], vcc
	v_max3_f32 v109, v109, v48, v49
	v_pk_mul_f32 v[110:111], v[82:83], v[80:81]
	v_add_u32_e32 v81, 47, v108
	v_sub_f32_e32 v42, v110, v111
	v_cndmask_b32_e32 v42, v106, v42, vcc
	v_cmp_gt_u32_e32 vcc, s33, v81
	v_cvt_f32_i32_e32 v81, v81
	v_mov_b32_e32 v82, v43
	s_and_b64 vcc, s[50:51], vcc
	v_pk_mul_f32 v[110:111], v[82:83], v[80:81]
	s_nop 0
	v_sub_f32_e32 v43, v110, v111
	v_add_u32_e32 v81, 46, v108
	v_cndmask_b32_e32 v43, v106, v43, vcc
	v_cmp_gt_u32_e32 vcc, s33, v81
	v_cvt_f32_i32_e32 v81, v81
	v_mov_b32_e32 v82, v44
	s_and_b64 vcc, s[52:53], vcc
	v_max3_f32 v109, v109, v42, v43
	v_pk_mul_f32 v[110:111], v[82:83], v[80:81]
	v_add_u32_e32 v81, 45, v108
	v_sub_f32_e32 v44, v110, v111
	v_cndmask_b32_e32 v44, v106, v44, vcc
	v_cmp_gt_u32_e32 vcc, s33, v81
	v_cvt_f32_i32_e32 v81, v81
	v_mov_b32_e32 v82, v45
	s_and_b64 vcc, s[54:55], vcc
	v_pk_mul_f32 v[110:111], v[82:83], v[80:81]
	s_nop 0
	v_sub_f32_e32 v45, v110, v111
	v_add_u32_e32 v81, 32, v108
	v_cndmask_b32_e32 v45, v106, v45, vcc
	v_cmp_gt_u32_e32 vcc, s33, v81
	v_cvt_f32_i32_e32 v81, v81
	v_mov_b32_e32 v82, v38
	s_and_b64 vcc, s[56:57], vcc
	v_max3_f32 v109, v109, v44, v45
	v_pk_mul_f32 v[110:111], v[82:83], v[80:81]
	v_add_u32_e32 v81, 31, v108
	v_sub_f32_e32 v38, v110, v111
	v_cndmask_b32_e32 v38, v106, v38, vcc
	v_cmp_gt_u32_e32 vcc, s33, v81
	v_cvt_f32_i32_e32 v81, v81
	v_mov_b32_e32 v82, v39
	s_and_b64 vcc, s[58:59], vcc
	v_pk_mul_f32 v[110:111], v[82:83], v[80:81]
	s_nop 0
	v_sub_f32_e32 v39, v110, v111
	v_add_u32_e32 v81, 30, v108
	v_cndmask_b32_e32 v39, v106, v39, vcc
	v_cmp_gt_u32_e32 vcc, s33, v81
	v_cvt_f32_i32_e32 v81, v81
	v_mov_b32_e32 v82, v40
	s_and_b64 vcc, s[60:61], vcc
	v_max3_f32 v109, v109, v38, v39
	v_pk_mul_f32 v[110:111], v[82:83], v[80:81]
	v_add_u32_e32 v81, 29, v108
	v_sub_f32_e32 v40, v110, v111
	v_cndmask_b32_e32 v40, v106, v40, vcc
	v_cmp_gt_u32_e32 vcc, s33, v81
	v_cvt_f32_i32_e32 v81, v81
	v_mov_b32_e32 v82, v41
	s_and_b64 vcc, s[62:63], vcc
	v_pk_mul_f32 v[110:111], v[82:83], v[80:81]
	s_nop 0
	v_sub_f32_e32 v41, v110, v111
	v_add_u32_e32 v81, 16, v108
	v_cndmask_b32_e32 v41, v106, v41, vcc
	v_cmp_gt_u32_e32 vcc, s33, v81
	v_cvt_f32_i32_e32 v81, v81
	v_mov_b32_e32 v82, v34
	s_and_b64 vcc, s[64:65], vcc
	v_max3_f32 v109, v109, v40, v41
	v_pk_mul_f32 v[110:111], v[82:83], v[80:81]
	v_add_u32_e32 v81, 15, v108
	v_sub_f32_e32 v34, v110, v111
	v_cndmask_b32_e32 v34, v106, v34, vcc
	v_cmp_gt_u32_e32 vcc, s33, v81
	v_cvt_f32_i32_e32 v81, v81
	v_mov_b32_e32 v82, v35
	s_and_b64 vcc, s[66:67], vcc
	v_pk_mul_f32 v[110:111], v[82:83], v[80:81]
	s_nop 0
	v_sub_f32_e32 v35, v110, v111
	v_add_u32_e32 v81, 14, v108
	v_cndmask_b32_e32 v35, v106, v35, vcc
	v_cmp_gt_u32_e32 vcc, s33, v81
	v_cvt_f32_i32_e32 v81, v81
	v_mov_b32_e32 v82, v36
	s_and_b64 vcc, s[68:69], vcc
	v_max3_f32 v109, v109, v34, v35
	v_pk_mul_f32 v[110:111], v[82:83], v[80:81]
	v_add_u32_e32 v81, 13, v108
	v_sub_f32_e32 v36, v110, v111
	v_cndmask_b32_e32 v36, v106, v36, vcc
	v_cmp_gt_u32_e32 vcc, s33, v81
	v_cvt_f32_i32_e32 v81, v81
	v_mov_b32_e32 v82, v37
	s_and_b64 vcc, s[70:71], vcc
	v_pk_mul_f32 v[110:111], v[82:83], v[80:81]
	v_cvt_f32_i32_e32 v81, v108
	v_mov_b32_e32 v82, v30
	v_sub_f32_e32 v37, v110, v111
	v_cndmask_b32_e32 v37, v106, v37, vcc
	v_pk_mul_f32 v[110:111], v[82:83], v[80:81]
	v_cmp_gt_u32_e32 vcc, s33, v108
	v_sub_f32_e32 v30, v110, v111
	v_add_u32_e32 v81, -1, v108
	v_cndmask_b32_e32 v30, v106, v30, vcc
; template <int D, int NKT, bool WIN> ...
;     ...
;         for (int j = 0; j < 4; ++j) { float v = s[kt][j] * scale;
;             if (WIN) { const int kpos = kbase + kt * 16 + fq * 4 + j, dist = qpos - kpos; const bool valid = (kpos >= 0) && (dist >= 0) && (dist < 128); v = valid ? v - slope * (float)dist : -1e30f; }
;             s[kt][j] = v; m = fmaxf(m, v); }
	v_cmp_gt_u32_e32 vcc, s33, v81
	v_cvt_f32_i32_e32 v81, v81
	v_mov_b32_e32 v82, v31
	v_max3_f32 v109, v109, v36, v37
	v_pk_mul_f32 v[110:111], v[82:83], v[80:81]
	s_nop 0
	v_sub_f32_e32 v31, v110, v111
	v_add_u32_e32 v81, -2, v108
	v_cndmask_b32_e32 v31, v106, v31, vcc
	v_cmp_gt_u32_e32 vcc, s33, v81
	v_cvt_f32_i32_e32 v81, v81
	v_mov_b32_e32 v82, v32
	v_max3_f32 v109, v109, v30, v31
	v_pk_mul_f32 v[110:111], v[82:83], v[80:81]
	s_nop 0
	v_sub_f32_e32 v32, v110, v111
	v_add_u32_e32 v81, -3, v108
	v_cndmask_b32_e32 v32, v106, v32, vcc
	v_cmp_gt_u32_e32 vcc, s33, v81
	v_cvt_f32_i32_e32 v81, v81
	v_mov_b32_e32 v82, v33
	v_pk_mul_f32 v[110:111], v[82:83], v[80:81]
	s_nop 0
	v_sub_f32_e32 v33, v110, v111
	v_add_u32_e32 v81, -16, v108
	v_cndmask_b32_e32 v33, v106, v33, vcc
	v_cmp_gt_u32_e32 vcc, s33, v81
	v_cvt_f32_i32_e32 v81, v81
	v_mov_b32_e32 v82, v26
	v_max3_f32 v109, v109, v32, v33
	v_pk_mul_f32 v[110:111], v[82:83], v[80:81]
	s_nop 0
	v_sub_f32_e32 v26, v110, v111
	v_subrev_u32_e32 v81, 17, v108
	v_cndmask_b32_e32 v26, v106, v26, vcc
	v_cmp_gt_u32_e32 vcc, s33, v81
	v_cvt_f32_i32_e32 v81, v81
	v_mov_b32_e32 v82, v27
	v_pk_mul_f32 v[110:111], v[82:83], v[80:81]
	s_nop 0
	v_sub_f32_e32 v27, v110, v111
	v_subrev_u32_e32 v81, 18, v108
	v_cndmask_b32_e32 v27, v106, v27, vcc
	v_cmp_gt_u32_e32 vcc, s33, v81
	v_cvt_f32_i32_e32 v81, v81
	v_mov_b32_e32 v82, v28
	v_max3_f32 v109, v109, v26, v27
	v_pk_mul_f32 v[110:111], v[82:83], v[80:81]
	s_nop 0
	v_sub_f32_e32 v28, v110, v111
	v_subrev_u32_e32 v81, 19, v108
	v_cndmask_b32_e32 v28, v106, v28, vcc
	v_cmp_gt_u32_e32 vcc, s33, v81
	v_cvt_f32_i32_e32 v81, v81
	v_mov_b32_e32 v82, v29
	v_pk_mul_f32 v[110:111], v[82:83], v[80:81]
	s_nop 0
	v_sub_f32_e32 v29, v110, v111
	v_subrev_u32_e32 v81, 32, v108
	v_cndmask_b32_e32 v29, v106, v29, vcc
	v_cmp_gt_u32_e32 vcc, s33, v81
	v_cvt_f32_i32_e32 v81, v81
	v_mov_b32_e32 v82, v22
	v_max3_f32 v109, v109, v28, v29
	v_pk_mul_f32 v[110:111], v[82:83], v[80:81]
	s_nop 0
	v_sub_f32_e32 v22, v110, v111
	v_subrev_u32_e32 v81, 33, v108
	v_cndmask_b32_e32 v22, v106, v22, vcc
	v_cmp_gt_u32_e32 vcc, s33, v81
	v_cvt_f32_i32_e32 v81, v81
	v_mov_b32_e32 v82, v23
	v_pk_mul_f32 v[110:111], v[82:83], v[80:81]
	s_nop 0
	v_sub_f32_e32 v23, v110, v111
	v_subrev_u32_e32 v81, 34, v108
	v_cndmask_b32_e32 v23, v106, v23, vcc
	v_cmp_gt_u32_e32 vcc, s33, v81
	v_cvt_f32_i32_e32 v81, v81
	v_mov_b32_e32 v82, v24
	v_max3_f32 v109, v109, v22, v23
	v_pk_mul_f32 v[110:111], v[82:83], v[80:81]
	s_nop 0
	v_sub_f32_e32 v24, v110, v111
	v_subrev_u32_e32 v81, 35, v108
	v_cndmask_b32_e32 v24, v106, v24, vcc
	v_cmp_gt_u32_e32 vcc, s33, v81
	v_cvt_f32_i32_e32 v81, v81
	v_mov_b32_e32 v82, v25
	v_pk_mul_f32 v[110:111], v[82:83], v[80:81]
	s_nop 0
	v_sub_f32_e32 v25, v110, v111
	v_subrev_u32_e32 v81, 48, v108
	v_cndmask_b32_e32 v25, v106, v25, vcc
	v_cmp_gt_u32_e32 vcc, s33, v81
	v_cvt_f32_i32_e32 v81, v81
	v_mov_b32_e32 v82, v18
	v_max3_f32 v109, v109, v24, v25
	v_pk_mul_f32 v[110:111], v[82:83], v[80:81]
	s_nop 0
	v_sub_f32_e32 v18, v110, v111
	v_subrev_u32_e32 v81, 49, v108
	v_cndmask_b32_e32 v18, v106, v18, vcc
	v_cmp_gt_u32_e32 vcc, s33, v81
	v_cvt_f32_i32_e32 v81, v81
	v_mov_b32_e32 v82, v19
	v_pk_mul_f32 v[110:111], v[82:83], v[80:81]
	s_nop 0
	v_sub_f32_e32 v19, v110, v111
	v_subrev_u32_e32 v81, 50, v108
	v_cndmask_b32_e32 v19, v106, v19, vcc
	v_cmp_gt_u32_e32 vcc, s33, v81
	v_cvt_f32_i32_e32 v81, v81
	v_mov_b32_e32 v82, v20
	v_max3_f32 v109, v109, v18, v19
	v_pk_mul_f32 v[110:111], v[82:83], v[80:81]
	s_nop 0
	v_sub_f32_e32 v20, v110, v111
	v_subrev_u32_e32 v81, 51, v108
	v_cndmask_b32_e32 v20, v106, v20, vcc
	v_cmp_gt_u32_e32 vcc, s33, v81
	v_cvt_f32_i32_e32 v81, v81
	v_mov_b32_e32 v82, v21
	v_pk_mul_f32 v[110:111], v[82:83], v[80:81]
	s_nop 0
	v_sub_f32_e32 v21, v110, v111
	v_subrev_u32_e32 v81, 64, v108
	v_cndmask_b32_e32 v21, v106, v21, vcc
	v_cmp_gt_u32_e32 vcc, s33, v81
	v_cvt_f32_i32_e32 v81, v81
	v_mov_b32_e32 v82, v14
	v_max3_f32 v109, v109, v20, v21
	v_pk_mul_f32 v[110:111], v[82:83], v[80:81]
	s_nop 0
	v_sub_f32_e32 v14, v110, v111
	v_add_u32_e32 v81, 0xffffffbf, v108
	v_cndmask_b32_e32 v14, v106, v14, vcc
	v_cmp_gt_u32_e32 vcc, s33, v81
	v_cvt_f32_i32_e32 v81, v81
	v_mov_b32_e32 v82, v15
	v_pk_mul_f32 v[110:111], v[82:83], v[80:81]
	s_nop 0
	v_sub_f32_e32 v15, v110, v111
	v_add_u32_e32 v81, 0xffffffbe, v108
	v_cndmask_b32_e32 v15, v106, v15, vcc
	v_cmp_gt_u32_e32 vcc, s33, v81
	v_cvt_f32_i32_e32 v81, v81
	v_mov_b32_e32 v82, v16
	v_max3_f32 v109, v109, v14, v15
	v_pk_mul_f32 v[110:111], v[82:83], v[80:81]
	s_nop 0
	v_sub_f32_e32 v16, v110, v111
	v_add_u32_e32 v81, 0xffffffbd, v108
	v_cndmask_b32_e32 v16, v106, v16, vcc
	v_cmp_gt_u32_e32 vcc, s33, v81
	v_cvt_f32_i32_e32 v81, v81
	v_mov_b32_e32 v82, v17
	v_pk_mul_f32 v[110:111], v[82:83], v[80:81]
	s_nop 0
	v_sub_f32_e32 v17, v110, v111
	v_add_u32_e32 v81, 0xffffffb0, v108
	v_cndmask_b32_e32 v17, v106, v17, vcc
	v_cmp_gt_u32_e32 vcc, s33, v81
	v_cvt_f32_i32_e32 v81, v81
	v_mov_b32_e32 v82, v10
	v_max3_f32 v109, v109, v16, v17
	v_pk_mul_f32 v[110:111], v[82:83], v[80:81]
	s_nop 0
	v_sub_f32_e32 v10, v110, v111
	v_add_u32_e32 v81, 0xffffffaf, v108
	v_cndmask_b32_e32 v10, v106, v10, vcc
	v_cmp_gt_u32_e32 vcc, s33, v81
	v_cvt_f32_i32_e32 v81, v81
	v_mov_b32_e32 v82, v11
	v_pk_mul_f32 v[110:111], v[82:83], v[80:81]
	s_nop 0
	v_sub_f32_e32 v11, v110, v111
	v_add_u32_e32 v81, 0xffffffae, v108
	v_cndmask_b32_e32 v11, v106, v11, vcc
	v_cmp_gt_u32_e32 vcc, s33, v81
	v_cvt_f32_i32_e32 v81, v81
	v_mov_b32_e32 v82, v12
	v_max3_f32 v109, v109, v10, v11
	v_pk_mul_f32 v[110:111], v[82:83], v[80:81]
	s_nop 0
	v_sub_f32_e32 v12, v110, v111
; template <int D, int NKT, bool WIN> ...
;     ...
;         for (int j = 0; j < 4; ++j) { float v = s[kt][j] * scale;
;             if (WIN) { const int kpos = kbase + kt * 16 + fq * 4 + j, dist = qpos - kpos; const bool valid = (kpos >= 0) && (dist >= 0) && (dist < 128); v = valid ? v - slope * (float)dist : -1e30f; }
;             s[kt][j] = v; m = fmaxf(m, v); }
;     m = fmaxf(m, __shfl_xor(m, 16)); m = fmaxf(m, __shfl_xor(m, 32));
;     if (WIN) m = fmaxf(m, sink);
;     float sum = 0.f;
; #pragma unroll
;     for (int kt = 0; kt < NKT; ++kt)
; #pragma unroll
;         for (int j = 0; j < 4; ++j) { const float pe = __expf(s[kt][j] - m); s[kt][j] = pe; sum += pe; }
;     sum += __shfl_xor(sum, 16); sum += __shfl_xor(sum, 32);
;     if (WIN) sum += __expf(sink - m);
	v_add_u32_e32 v81, 0xffffffad, v108
	v_cndmask_b32_e32 v12, v106, v12, vcc
	v_cmp_gt_u32_e32 vcc, s33, v81
	v_cvt_f32_i32_e32 v81, v81
	v_mov_b32_e32 v82, v13
	v_pk_mul_f32 v[110:111], v[82:83], v[80:81]
	s_nop 0
	v_sub_f32_e32 v13, v110, v111
	v_add_u32_e32 v81, 0xffffffa0, v108
	v_cndmask_b32_e32 v13, v106, v13, vcc
	v_cmp_gt_u32_e32 vcc, s33, v81
	v_cvt_f32_i32_e32 v81, v81
	v_mov_b32_e32 v82, v6
	v_max3_f32 v109, v109, v12, v13
	v_pk_mul_f32 v[110:111], v[82:83], v[80:81]
	s_nop 0
	v_sub_f32_e32 v6, v110, v111
	v_add_u32_e32 v81, 0xffffff9f, v108
	v_cndmask_b32_e32 v6, v106, v6, vcc
	v_cmp_gt_u32_e32 vcc, s33, v81
	v_cvt_f32_i32_e32 v81, v81
	v_mov_b32_e32 v82, v7
	v_pk_mul_f32 v[110:111], v[82:83], v[80:81]
	s_nop 0
	v_sub_f32_e32 v7, v110, v111
	v_add_u32_e32 v81, 0xffffff9e, v108
	v_cndmask_b32_e32 v7, v106, v7, vcc
	v_cmp_gt_u32_e32 vcc, s33, v81
	v_cvt_f32_i32_e32 v81, v81
	v_mov_b32_e32 v82, v8
	v_max3_f32 v112, v109, v6, v7
	v_pk_mul_f32 v[110:111], v[82:83], v[80:81]
	s_nop 0
	v_sub_f32_e32 v8, v110, v111
	v_add_u32_e32 v81, 0xffffff9d, v108
	v_cndmask_b32_e32 v8, v106, v8, vcc
	v_cmp_gt_u32_e32 vcc, s33, v81
	v_cvt_f32_i32_e32 v81, v81
	v_mov_b32_e32 v82, v9
	v_pk_mul_f32 v[110:111], v[82:83], v[80:81]
	s_nop 0
	v_sub_f32_e32 v9, v110, v111
	v_add_u32_e32 v81, 0xffffff90, v108
	v_cndmask_b32_e32 v109, v106, v9, vcc
	v_cmp_gt_u32_e32 vcc, s33, v81
	v_cvt_f32_i32_e32 v81, v81
	v_mov_b32_e32 v82, v2
	v_max3_f32 v9, v112, v8, v109
	v_pk_mul_f32 v[110:111], v[82:83], v[80:81]
	s_nop 0
	v_sub_f32_e32 v2, v110, v111
	v_add_u32_e32 v81, 0xffffff8f, v108
	v_cndmask_b32_e32 v2, v106, v2, vcc
	v_cmp_gt_u32_e32 vcc, s33, v81
	v_cvt_f32_i32_e32 v81, v81
	v_mov_b32_e32 v82, v3
	v_pk_mul_f32 v[110:111], v[82:83], v[80:81]
	s_nop 0
	v_sub_f32_e32 v3, v110, v111
	v_cndmask_b32_e32 v110, v106, v3, vcc
	v_max3_f32 v3, v9, v2, v110
	v_add_u32_e32 v9, 0xffffff8e, v108
	v_cvt_f32_i32_e32 v81, v9
	v_mov_b32_e32 v82, v4
	v_cmp_gt_u32_e32 vcc, s33, v9
	v_pk_mul_f32 v[112:113], v[82:83], v[80:81]
	s_nop 0
	v_sub_f32_e32 v4, v112, v113
	v_cndmask_b32_e32 v111, v106, v4, vcc
	v_add_u32_e32 v4, 0xffffff8d, v108
	v_cvt_f32_i32_e32 v81, v4
	v_mov_b32_e32 v82, v5
	v_cmp_gt_u32_e32 vcc, s33, v4
	v_pk_mul_f32 v[4:5], v[82:83], v[80:81]
	s_nop 0
	v_sub_f32_e32 v4, v4, v5
	v_cndmask_b32_e32 v82, v106, v4, vcc
	v_max3_f32 v3, v3, v111, v82
	ds_bpermute_b32 v4, v92, v3
	s_waitcnt lgkmcnt(0)
	v_max_f32_e32 v4, v4, v4
	v_max_f32_e32 v3, v3, v4
	ds_bpermute_b32 v4, v93, v3
	s_waitcnt lgkmcnt(0)
	v_max3_f32 v81, v3, v4, v107
	v_sub_f32_e32 v4, v63, v81
	v_mul_f32_e32 v4, 0x3fb8aa3b, v4
	v_exp_f32_e32 v63, v4
	v_sub_f32_e32 v4, v64, v81
	v_mul_f32_e32 v4, 0x3fb8aa3b, v4
	v_exp_f32_e32 v64, v4
	v_sub_f32_e32 v4, v65, v81
	v_sub_f32_e32 v3, v62, v81
	v_mul_f32_e32 v4, 0x3fb8aa3b, v4
	v_mul_f32_e32 v3, 0x3fb8aa3b, v3
	v_exp_f32_e32 v65, v4
	v_sub_f32_e32 v4, v58, v81
	v_exp_f32_e32 v62, v3
	v_mul_f32_e32 v4, 0x3fb8aa3b, v4
	v_exp_f32_e32 v108, v4
	v_sub_f32_e32 v4, v59, v81
	v_mul_f32_e32 v4, 0x3fb8aa3b, v4
	v_exp_f32_e32 v59, v4
	v_sub_f32_e32 v4, v60, v81
	v_add_f32_e32 v3, 0, v62
	v_mul_f32_e32 v4, 0x3fb8aa3b, v4
	v_add_f32_e32 v3, v63, v3
	v_exp_f32_e32 v60, v4
	v_sub_f32_e32 v4, v61, v81
	v_add_f32_e32 v3, v64, v3
	v_mul_f32_e32 v4, 0x3fb8aa3b, v4
	v_add_f32_e32 v3, v65, v3
	v_exp_f32_e32 v61, v4
	v_add_f32_e32 v3, v108, v3
	v_add_f32_e32 v3, v59, v3
	v_sub_f32_e32 v9, v56, v81
	v_add_f32_e32 v3, v60, v3
	v_mul_f32_e32 v9, 0x3fb8aa3b, v9
	v_add_f32_e32 v4, v61, v3
	v_sub_f32_e32 v3, v54, v81
	v_exp_f32_e32 v54, v9
	v_sub_f32_e32 v9, v57, v81
	v_mul_f32_e32 v9, 0x3fb8aa3b, v9
	v_mul_f32_e32 v3, 0x3fb8aa3b, v3
	v_sub_f32_e32 v5, v55, v81
	v_exp_f32_e32 v55, v9
	v_sub_f32_e32 v9, v50, v81
	v_exp_f32_e32 v3, v3
	v_mul_f32_e32 v5, 0x3fb8aa3b, v5
	v_mul_f32_e32 v9, 0x3fb8aa3b, v9
	v_exp_f32_e32 v5, v5
	v_exp_f32_e32 v50, v9
	v_sub_f32_e32 v9, v51, v81
	v_mul_f32_e32 v9, 0x3fb8aa3b, v9
	v_exp_f32_e32 v51, v9
	v_sub_f32_e32 v9, v52, v81
	v_add_f32_e32 v4, v3, v4
	v_mul_f32_e32 v9, 0x3fb8aa3b, v9
	v_add_f32_e32 v4, v5, v4
	v_exp_f32_e32 v52, v9
	v_sub_f32_e32 v9, v53, v81
	v_add_f32_e32 v4, v54, v4
	v_mul_f32_e32 v9, 0x3fb8aa3b, v9
	v_add_f32_e32 v4, v55, v4
	v_exp_f32_e32 v53, v9
	v_add_f32_e32 v4, v50, v4
	v_add_f32_e32 v4, v51, v4
	v_add_f32_e32 v4, v52, v4
	v_add_f32_e32 v9, v53, v4
	v_sub_f32_e32 v4, v46, v81
	v_mul_f32_e32 v4, 0x3fb8aa3b, v4
	v_sub_f32_e32 v46, v47, v81
	v_exp_f32_e32 v4, v4
	v_mul_f32_e32 v46, 0x3fb8aa3b, v46
	v_sub_f32_e32 v47, v48, v81
	v_exp_f32_e32 v46, v46
	v_mul_f32_e32 v47, 0x3fb8aa3b, v47
	v_sub_f32_e32 v48, v49, v81
	v_exp_f32_e32 v47, v47
	v_mul_f32_e32 v48, 0x3fb8aa3b, v48
	v_sub_f32_e32 v42, v42, v81
	v_exp_f32_e32 v48, v48
	v_mul_f32_e32 v42, 0x3fb8aa3b, v42
	v_sub_f32_e32 v43, v43, v81
	v_add_f32_e32 v9, v4, v9
	v_exp_f32_e32 v42, v42
	v_mul_f32_e32 v43, 0x3fb8aa3b, v43
	v_sub_f32_e32 v44, v44, v81
	v_add_f32_e32 v9, v46, v9
	v_exp_f32_e32 v43, v43
	v_mul_f32_e32 v44, 0x3fb8aa3b, v44
	v_sub_f32_e32 v45, v45, v81
	v_add_f32_e32 v9, v47, v9
	v_exp_f32_e32 v44, v44
	v_mul_f32_e32 v45, 0x3fb8aa3b, v45
	v_add_f32_e32 v9, v48, v9
	v_exp_f32_e32 v45, v45
	v_add_f32_e32 v9, v42, v9
	v_add_f32_e32 v9, v43, v9
	v_add_f32_e32 v9, v44, v9
	v_add_f32_e32 v49, v45, v9
	v_sub_f32_e32 v9, v38, v81
	v_mul_f32_e32 v9, 0x3fb8aa3b, v9
	v_sub_f32_e32 v38, v39, v81
	v_exp_f32_e32 v9, v9
	v_mul_f32_e32 v38, 0x3fb8aa3b, v38
	v_sub_f32_e32 v39, v40, v81
	v_exp_f32_e32 v38, v38
	v_mul_f32_e32 v39, 0x3fb8aa3b, v39
	v_sub_f32_e32 v40, v41, v81
	v_exp_f32_e32 v39, v39
	v_mul_f32_e32 v40, 0x3fb8aa3b, v40
	v_sub_f32_e32 v34, v34, v81
	v_exp_f32_e32 v40, v40
; #define LAS __attribute__((address_space(3)))
; __device__ __forceinline__ unsigned pk2(float lo, float hi) { f32x2 v = {lo, hi}; bf16x2_t b = __builtin_convertvector(v, bf16x2_t); return __builtin_bit_cast(unsigned, b); }
; #define MFMA16(a, b, c) __builtin_amdgcn_mfma_f32_16x16x32_bf16((a), (b), (c), 0, 0, 0)
; template <int D, int NKT, bool WIN> ...
;     ...
;     for (int kt = 0; kt < NKT; ++kt)
; #pragma unroll
;         for (int j = 0; j < 4; ++j) { const float pe = __expf(s[kt][j] - m); s[kt][j] = pe; sum += pe; }
;     sum += __shfl_xor(sum, 16); sum += __shfl_xor(sum, 32);
;     if (WIN) sum += __expf(sink - m);
;     const float inv = 1.0f / sum;
; #pragma unroll
;     for (int dt = 0; dt < D / 16; ++dt) o[dt] = (f32x4){0.f, 0.f, 0.f, 0.f};
; #pragma unroll
;     for (int kk = 0; kk < NKT / 2; ++kk) {
;         u32x4 pw; pw.x = pk2(s[2 * kk][0], s[2 * kk][1]); pw.y = pk2(s[2 * kk][2], s[2 * kk][3]); pw.z = pk2(s[2 * kk + 1][0], s[2 * kk + 1][1]); pw.w = pk2(s[2 * kk + 1][2], s[2 * kk + 1][3]);
;         const bf16x8 pf = __builtin_bit_cast(bf16x8, pw);
; #pragma unroll
;         for (int dt = 0; dt < D / 16; ++dt) {
;             const u32x2 lo = *(const LAS u32x2*)(Vl + (dt * 16 + fr) * vstr + ((2 * kk) * 16 + fq * 4) * 2), hi = *(const LAS u32x2*)(Vl + (dt * 16 + fr) * vstr + ((2 * kk + 1) * 16 + fq * 4) * 2);
;             u32x4 aw; aw.x = lo.x; aw.y = lo.y; aw.z = hi.x; aw.w = hi.y;
;             o[dt] = MFMA16(__builtin_bit_cast(bf16x8, aw), pf, o[dt]); }
	v_mul_f32_e32 v34, 0x3fb8aa3b, v34
	v_sub_f32_e32 v35, v35, v81
	v_add_f32_e32 v49, v9, v49
	v_exp_f32_e32 v34, v34
	v_mul_f32_e32 v35, 0x3fb8aa3b, v35
	v_sub_f32_e32 v36, v36, v81
	v_add_f32_e32 v49, v38, v49
	v_exp_f32_e32 v35, v35
	v_mul_f32_e32 v36, 0x3fb8aa3b, v36
	v_sub_f32_e32 v37, v37, v81
	v_add_f32_e32 v49, v39, v49
	v_exp_f32_e32 v36, v36
	v_mul_f32_e32 v37, 0x3fb8aa3b, v37
	v_sub_f32_e32 v30, v30, v81
	v_add_f32_e32 v41, v40, v49
	v_exp_f32_e32 v37, v37
	v_mul_f32_e32 v30, 0x3fb8aa3b, v30
	v_sub_f32_e32 v31, v31, v81
	v_add_f32_e32 v41, v34, v41
	v_exp_f32_e32 v30, v30
	v_mul_f32_e32 v31, 0x3fb8aa3b, v31
	v_sub_f32_e32 v32, v32, v81
	v_add_f32_e32 v41, v35, v41
	v_exp_f32_e32 v31, v31
	v_mul_f32_e32 v32, 0x3fb8aa3b, v32
	v_sub_f32_e32 v33, v33, v81
	v_add_f32_e32 v41, v36, v41
	v_exp_f32_e32 v32, v32
	v_mul_f32_e32 v33, 0x3fb8aa3b, v33
	v_sub_f32_e32 v26, v26, v81
	v_add_f32_e32 v41, v37, v41
	v_exp_f32_e32 v33, v33
	v_mul_f32_e32 v26, 0x3fb8aa3b, v26
	v_sub_f32_e32 v27, v27, v81
	v_add_f32_e32 v41, v30, v41
	v_exp_f32_e32 v26, v26
	v_mul_f32_e32 v27, 0x3fb8aa3b, v27
	v_sub_f32_e32 v28, v28, v81
	v_add_f32_e32 v41, v31, v41
	v_exp_f32_e32 v27, v27
	v_mul_f32_e32 v28, 0x3fb8aa3b, v28
	v_add_f32_e32 v41, v32, v41
	v_exp_f32_e32 v28, v28
	v_add_f32_e32 v41, v33, v41
	v_add_f32_e32 v41, v26, v41
	v_sub_f32_e32 v29, v29, v81
	v_add_f32_e32 v41, v27, v41
	v_mul_f32_e32 v29, 0x3fb8aa3b, v29
	v_sub_f32_e32 v22, v22, v81
	v_add_f32_e32 v49, v28, v41
	v_exp_f32_e32 v41, v29
	v_mul_f32_e32 v22, 0x3fb8aa3b, v22
	v_sub_f32_e32 v23, v23, v81
	v_exp_f32_e32 v22, v22
	v_mul_f32_e32 v23, 0x3fb8aa3b, v23
	v_sub_f32_e32 v24, v24, v81
	v_exp_f32_e32 v23, v23
	v_mul_f32_e32 v24, 0x3fb8aa3b, v24
	v_sub_f32_e32 v25, v25, v81
	v_exp_f32_e32 v24, v24
	v_mul_f32_e32 v25, 0x3fb8aa3b, v25
	v_sub_f32_e32 v18, v18, v81
	v_add_f32_e32 v29, v41, v49
	v_exp_f32_e32 v25, v25
	v_mul_f32_e32 v18, 0x3fb8aa3b, v18
	v_sub_f32_e32 v19, v19, v81
	v_add_f32_e32 v29, v22, v29
	v_exp_f32_e32 v18, v18
	v_mul_f32_e32 v19, 0x3fb8aa3b, v19
	v_sub_f32_e32 v20, v20, v81
	v_add_f32_e32 v29, v23, v29
	v_exp_f32_e32 v19, v19
	v_mul_f32_e32 v20, 0x3fb8aa3b, v20
	v_sub_f32_e32 v21, v21, v81
	v_add_f32_e32 v29, v24, v29
	v_exp_f32_e32 v20, v20
	v_mul_f32_e32 v21, 0x3fb8aa3b, v21
	v_sub_f32_e32 v14, v14, v81
	v_add_f32_e32 v29, v25, v29
	v_exp_f32_e32 v56, v21
	v_mul_f32_e32 v14, 0x3fb8aa3b, v14
	v_sub_f32_e32 v15, v15, v81
	v_add_f32_e32 v29, v18, v29
	v_exp_f32_e32 v14, v14
	v_mul_f32_e32 v15, 0x3fb8aa3b, v15
	v_sub_f32_e32 v16, v16, v81
	v_add_f32_e32 v29, v19, v29
	v_exp_f32_e32 v15, v15
	v_mul_f32_e32 v16, 0x3fb8aa3b, v16
	v_sub_f32_e32 v17, v17, v81
	v_add_f32_e32 v29, v20, v29
	v_exp_f32_e32 v16, v16
	v_mul_f32_e32 v17, 0x3fb8aa3b, v17
	v_sub_f32_e32 v10, v10, v81
	v_add_f32_e32 v21, v56, v29
	v_exp_f32_e32 v17, v17
	v_mul_f32_e32 v10, 0x3fb8aa3b, v10
	v_add_f32_e32 v21, v14, v21
	v_exp_f32_e32 v10, v10
	v_add_f32_e32 v21, v15, v21
	v_add_f32_e32 v21, v16, v21
	v_sub_f32_e32 v11, v11, v81
	v_add_f32_e32 v21, v17, v21
	v_mul_f32_e32 v11, 0x3fb8aa3b, v11
	v_add_f32_e32 v29, v10, v21
	v_exp_f32_e32 v21, v11
	v_sub_f32_e32 v12, v12, v81
	v_mul_f32_e32 v12, 0x3fb8aa3b, v12
	v_sub_f32_e32 v6, v6, v81
	v_add_f32_e32 v11, v21, v29
	v_exp_f32_e32 v29, v12
	v_sub_f32_e32 v12, v13, v81
	v_mul_f32_e32 v12, 0x3fb8aa3b, v12
	v_exp_f32_e32 v57, v12
	v_mul_f32_e32 v6, 0x3fb8aa3b, v6
	v_sub_f32_e32 v7, v7, v81
	v_exp_f32_e32 v6, v6
	v_mul_f32_e32 v7, 0x3fb8aa3b, v7
	v_sub_f32_e32 v8, v8, v81
	v_exp_f32_e32 v7, v7
	v_mul_f32_e32 v8, 0x3fb8aa3b, v8
	v_add_f32_e32 v11, v29, v11
	v_exp_f32_e32 v8, v8
	v_add_f32_e32 v11, v57, v11
	v_add_f32_e32 v11, v6, v11
	v_add_f32_e32 v11, v7, v11
	v_add_f32_e32 v12, v8, v11
	v_sub_f32_e32 v11, v109, v81
	v_mul_f32_e32 v11, 0x3fb8aa3b, v11
	v_exp_f32_e32 v11, v11
	v_sub_f32_e32 v2, v2, v81
	v_mul_f32_e32 v2, 0x3fb8aa3b, v2
	v_cvt_pk_bf16_f32 v112, v108, v59
	v_add_f32_e32 v13, v11, v12
	v_exp_f32_e32 v12, v2
	v_add_u32_e32 v108, v90, v70
	v_add_u32_e32 v59, 0x9000, v108
	v_cvt_pk_bf16_f32 v113, v60, v61
	v_add_f32_e32 v2, v12, v13
	v_sub_f32_e32 v13, v110, v81
	v_cvt_pk_bf16_f32 v110, v62, v63
	ds_read2_b64 v[60:63], v59 offset1:4
	v_sub_f32_e32 v49, v111, v81
	v_cvt_pk_bf16_f32 v111, v64, v65
	v_mul_f32_e32 v13, 0x3fb8aa3b, v13
	v_exp_f32_e32 v13, v13
	s_waitcnt lgkmcnt(0)
	v_mfma_f32_16x16x32_bf16 v[114:117], v[60:63], v[110:113], 0
	v_add_u32_e32 v60, 0xb000, v108
	ds_read2_b64 v[62:65], v60 offset0:16 offset1:20
	v_add_u32_e32 v61, 0xd000, v108
	v_mul_f32_e32 v49, 0x3fb8aa3b, v49
	v_sub_f32_e32 v58, v82, v81
	s_waitcnt lgkmcnt(0)
	v_mfma_f32_16x16x32_bf16 v[118:121], v[62:65], v[110:113], 0
	ds_read2_b64 v[62:65], v61 offset0:32 offset1:36
	v_exp_f32_e32 v49, v49
	v_mul_f32_e32 v58, 0x3fb8aa3b, v58
	v_exp_f32_e32 v58, v58
	v_add_f32_e32 v2, v13, v2
	v_add_f32_e32 v2, v49, v2
	v_add_u32_e32 v109, v91, v70
	v_add_f32_e32 v2, v58, v2
	ds_bpermute_b32 v82, v92, v2
	s_waitcnt lgkmcnt(1)
	v_mfma_f32_16x16x32_bf16 v[122:125], v[62:65], v[110:113], 0
	v_add_u32_e32 v62, 0x9000, v109
	ds_read2_b64 v[126:129], v62 offset1:4
	v_sub_f32_e32 v81, v107, v81
	s_waitcnt lgkmcnt(1)
	v_add_f32_e32 v2, v2, v82
	ds_bpermute_b32 v82, v93, v2
	v_mul_f32_e32 v81, 0x3fb8aa3b, v81
	v_exp_f32_e32 v81, v81
	s_waitcnt lgkmcnt(1)
	v_mfma_f32_16x16x32_bf16 v[110:113], v[126:129], v[110:113], 0
	s_waitcnt lgkmcnt(0)
	v_add_f32_e32 v2, v2, v82
	v_add_f32_e32 v2, v81, v2
	v_cvt_pk_bf16_f32 v128, v50, v51
	v_cvt_pk_bf16_f32 v129, v52, v53
	ds_read2_b64 v[50:53], v59 offset0:8 offset1:12
	v_cvt_pk_bf16_f32 v126, v3, v5
	v_cvt_pk_bf16_f32 v127, v54, v55
	s_waitcnt lgkmcnt(0)
; #define LAS __attribute__((address_space(3)))
; __device__ __forceinline__ unsigned pk2(float lo, float hi) { f32x2 v = {lo, hi}; bf16x2_t b = __builtin_convertvector(v, bf16x2_t); return __builtin_bit_cast(unsigned, b); }
; #define MFMA16(a, b, c) __builtin_amdgcn_mfma_f32_16x16x32_bf16((a), (b), (c), 0, 0, 0)
; template <int D, int NKT, bool WIN> ...
;     ...
;     for (int kk = 0; kk < NKT / 2; ++kk) {
;         u32x4 pw; pw.x = pk2(s[2 * kk][0], s[2 * kk][1]); pw.y = pk2(s[2 * kk][2], s[2 * kk][3]); pw.z = pk2(s[2 * kk + 1][0], s[2 * kk + 1][1]); pw.w = pk2(s[2 * kk + 1][2], s[2 * kk + 1][3]);
;         const bf16x8 pf = __builtin_bit_cast(bf16x8, pw);
; #pragma unroll
;         for (int dt = 0; dt < D / 16; ++dt) {
;             const u32x2 lo = *(const LAS u32x2*)(Vl + (dt * 16 + fr) * vstr + ((2 * kk) * 16 + fq * 4) * 2), hi = *(const LAS u32x2*)(Vl + (dt * 16 + fr) * vstr + ((2 * kk + 1) * 16 + fq * 4) * 2);
;             u32x4 aw; aw.x = lo.x; aw.y = lo.y; aw.z = hi.x; aw.w = hi.y;
;             o[dt] = MFMA16(__builtin_bit_cast(bf16x8, aw), pf, o[dt]); }
;         __builtin_amdgcn_sched_barrier(0);
;     }
; #pragma unroll
;     for (int dt = 0; dt < D / 16; ++dt) o[dt] = o[dt] * inv;
; __device__ __forceinline__ void win_attn_prompt_unit(int unit, const bf16* Z, bf16* HB, const float* sinks, LAS unsigned char* lds, int tid, int wave, int lane) {
;     ...
; #pragma unroll
;         for (int dt = 0; dt < 4; ++dt) { u32x2 w; w.x = pk2(o[dt][0], o[dt][1]); w.y = pk2(o[dt][2], o[dt][3]); *(u32x2*)(HB + row * DM + hq * 64 + dt * 16 + fq * 4) = w; } }
	s_nop 0
	v_mfma_f32_16x16x32_bf16 v[50:53], v[50:53], v[126:129], v[114:117]
	s_nop 2
	ds_read2_b64 v[114:117], v60 offset0:24 offset1:28
	s_waitcnt lgkmcnt(0)
	v_mfma_f32_16x16x32_bf16 v[114:117], v[114:117], v[126:129], v[118:121]
	s_nop 2
	ds_read2_b64 v[118:121], v61 offset0:40 offset1:44
	s_waitcnt lgkmcnt(0)
	v_mfma_f32_16x16x32_bf16 v[118:121], v[118:121], v[126:129], v[122:125]
	s_nop 2
	ds_read2_b64 v[122:125], v62 offset0:8 offset1:12
	s_waitcnt lgkmcnt(0)
	v_mfma_f32_16x16x32_bf16 v[110:113], v[122:125], v[126:129], v[110:113]
	v_cvt_pk_bf16_f32 v124, v42, v43
	v_cvt_pk_bf16_f32 v125, v44, v45
	ds_read2_b64 v[42:45], v59 offset0:16 offset1:20
	v_cvt_pk_bf16_f32 v122, v4, v46
	v_cvt_pk_bf16_f32 v123, v47, v48
	s_waitcnt lgkmcnt(0)
	s_nop 0
	v_mfma_f32_16x16x32_bf16 v[42:45], v[42:45], v[122:125], v[50:53]
	s_nop 2
	ds_read2_b64 v[50:53], v60 offset0:32 offset1:36
	s_waitcnt lgkmcnt(0)
	v_mfma_f32_16x16x32_bf16 v[50:53], v[50:53], v[122:125], v[114:117]
	s_nop 2
	ds_read2_b64 v[114:117], v61 offset0:48 offset1:52
	s_waitcnt lgkmcnt(0)
	v_mfma_f32_16x16x32_bf16 v[114:117], v[114:117], v[122:125], v[118:121]
	s_nop 2
	ds_read2_b64 v[118:121], v62 offset0:16 offset1:20
	s_waitcnt lgkmcnt(0)
	v_mfma_f32_16x16x32_bf16 v[110:113], v[118:121], v[122:125], v[110:113]
	v_cvt_pk_bf16_f32 v120, v34, v35
	v_cvt_pk_bf16_f32 v121, v36, v37
	ds_read2_b64 v[34:37], v59 offset0:24 offset1:28
	v_cvt_pk_bf16_f32 v118, v9, v38
	v_cvt_pk_bf16_f32 v119, v39, v40
	s_waitcnt lgkmcnt(0)
	s_nop 0
	v_mfma_f32_16x16x32_bf16 v[34:37], v[34:37], v[118:121], v[42:45]
	s_nop 2
	ds_read2_b64 v[42:45], v60 offset0:40 offset1:44
	s_waitcnt lgkmcnt(0)
	v_mfma_f32_16x16x32_bf16 v[42:45], v[42:45], v[118:121], v[50:53]
	s_nop 2
	ds_read2_b64 v[50:53], v61 offset0:56 offset1:60
	s_waitcnt lgkmcnt(0)
	v_mfma_f32_16x16x32_bf16 v[50:53], v[50:53], v[118:121], v[114:117]
	s_nop 2
	ds_read2_b64 v[114:117], v62 offset0:24 offset1:28
	s_waitcnt lgkmcnt(0)
	v_mfma_f32_16x16x32_bf16 v[110:113], v[114:117], v[118:121], v[110:113]
	v_cvt_pk_bf16_f32 v30, v30, v31
	v_cvt_pk_bf16_f32 v31, v32, v33
	v_cvt_pk_bf16_f32 v33, v28, v41
	ds_read2_b64 v[38:41], v59 offset0:32 offset1:36
	v_cvt_pk_bf16_f32 v32, v26, v27
	s_waitcnt lgkmcnt(0)
	s_nop 0
	v_mfma_f32_16x16x32_bf16 v[34:37], v[38:41], v[30:33], v[34:37]
	ds_read2_b64 v[38:41], v60 offset0:48 offset1:52
	s_waitcnt lgkmcnt(0)
	v_mfma_f32_16x16x32_bf16 v[38:41], v[38:41], v[30:33], v[42:45]
	s_nop 2
	ds_read2_b64 v[42:45], v61 offset0:64 offset1:68
	s_waitcnt lgkmcnt(0)
	v_mfma_f32_16x16x32_bf16 v[42:45], v[42:45], v[30:33], v[50:53]
	s_nop 2
	ds_read2_b64 v[50:53], v62 offset0:32 offset1:36
	s_waitcnt lgkmcnt(0)
	v_mfma_f32_16x16x32_bf16 v[30:33], v[50:53], v[30:33], v[110:113]
	ds_read2_b64 v[50:53], v59 offset0:40 offset1:44
	v_cvt_pk_bf16_f32 v22, v22, v23
	v_cvt_pk_bf16_f32 v23, v24, v25
	v_cvt_pk_bf16_f32 v24, v18, v19
	v_cvt_pk_bf16_f32 v25, v20, v56
	s_waitcnt lgkmcnt(0)
	s_nop 0
	v_mfma_f32_16x16x32_bf16 v[34:37], v[50:53], v[22:25], v[34:37]
	ds_read2_b64 v[50:53], v60 offset0:56 offset1:60
	s_waitcnt lgkmcnt(0)
	v_mfma_f32_16x16x32_bf16 v[38:41], v[50:53], v[22:25], v[38:41]
	ds_read2_b64 v[50:53], v61 offset0:72 offset1:76
	s_waitcnt lgkmcnt(0)
	v_mfma_f32_16x16x32_bf16 v[42:45], v[50:53], v[22:25], v[42:45]
	ds_read2_b64 v[50:53], v62 offset0:40 offset1:44
	s_waitcnt lgkmcnt(0)
	v_mfma_f32_16x16x32_bf16 v[22:25], v[50:53], v[22:25], v[30:33]
	v_cvt_pk_bf16_f32 v14, v14, v15
	v_cvt_pk_bf16_f32 v15, v16, v17
	v_cvt_pk_bf16_f32 v16, v10, v21
	ds_read2_b64 v[18:21], v59 offset0:48 offset1:52
	v_cvt_pk_bf16_f32 v17, v29, v57
	ds_read2_b64 v[26:29], v60 offset0:64 offset1:68
	ds_read2_b64 v[30:33], v61 offset0:80 offset1:84
	s_waitcnt lgkmcnt(2)
	v_mfma_f32_16x16x32_bf16 v[18:21], v[18:21], v[14:17], v[34:37]
	s_nop 2
	ds_read2_b64 v[34:37], v62 offset0:48 offset1:52
	s_waitcnt lgkmcnt(2)
	v_mfma_f32_16x16x32_bf16 v[26:29], v[26:29], v[14:17], v[38:41]
	s_waitcnt lgkmcnt(1)
	v_mfma_f32_16x16x32_bf16 v[30:33], v[30:33], v[14:17], v[42:45]
	s_waitcnt lgkmcnt(0)
	v_mfma_f32_16x16x32_bf16 v[14:17], v[34:37], v[14:17], v[22:25]
	v_cvt_pk_bf16_f32 v5, v8, v11
	ds_read2_b64 v[8:11], v59 offset0:56 offset1:60
	v_cvt_pk_bf16_f32 v4, v6, v7
	v_cvt_pk_bf16_f32 v6, v12, v13
	v_cvt_pk_bf16_f32 v7, v49, v58
	ds_read2_b64 v[22:25], v61 offset0:88 offset1:92
	s_waitcnt lgkmcnt(1)
	v_mfma_f32_16x16x32_bf16 v[8:11], v[8:11], v[4:7], v[18:21]
	s_nop 2
	ds_read2_b64 v[18:21], v60 offset0:72 offset1:76
	s_waitcnt lgkmcnt(1)
	v_mfma_f32_16x16x32_bf16 v[22:25], v[22:25], v[4:7], v[30:33]
	s_waitcnt lgkmcnt(0)
	v_mfma_f32_16x16x32_bf16 v[18:21], v[18:21], v[4:7], v[26:29]
	s_nop 2
	ds_read2_b64 v[26:29], v62 offset0:56 offset1:60
	s_waitcnt lgkmcnt(0)
	v_mfma_f32_16x16x32_bf16 v[4:7], v[26:29], v[4:7], v[14:17]
	v_div_scale_f32 v3, vcc, v2, v2, 1.0
	v_rcp_f32_e32 v13, v3
	v_div_scale_f32 v12, vcc, 1.0, v2, 1.0
	s_mov_b64 s[96:97], 0x2c000
	v_fma_f32 v14, -v3, v13, 1.0
	v_fmac_f32_e32 v13, v14, v13
	v_mul_f32_e32 v14, v12, v13
	v_fma_f32 v15, -v3, v14, v12
	v_fmac_f32_e32 v14, v15, v13
	v_fma_f32 v3, -v3, v14, v12
	v_div_fmas_f32 v3, v3, v13, v14
	v_div_fixup_f32 v2, v3, v2, 1.0
	v_pk_mul_f32 v[10:11], v[2:3], v[10:11] op_sel_hi:[0,1]
	v_pk_mul_f32 v[8:9], v[2:3], v[8:9] op_sel_hi:[0,1]
	s_add_i32 s0, s0, 16
	v_lshl_add_u64 v[86:87], v[86:87], 0, s[96:97]
	v_pk_mul_f32 v[12:13], v[2:3], v[20:21] op_sel_hi:[0,1]
	v_pk_mul_f32 v[14:15], v[2:3], v[18:19] op_sel_hi:[0,1]
	v_pk_mul_f32 v[16:17], v[2:3], v[24:25] op_sel_hi:[0,1]
	v_pk_mul_f32 v[18:19], v[2:3], v[22:23] op_sel_hi:[0,1]
	v_pk_mul_f32 v[6:7], v[2:3], v[6:7] op_sel_hi:[0,1]
	v_pk_mul_f32 v[2:3], v[2:3], v[4:5] op_sel_hi:[0,1]
	v_cvt_pk_bf16_f32 v4, v8, v9
	v_cvt_pk_bf16_f32 v5, v10, v11
	s_mov_b64 s[96:97], 0x10000
	s_cmp_lg_u32 s0, 64
	v_cvt_pk_bf16_f32 v8, v14, v15
	v_cvt_pk_bf16_f32 v9, v12, v13
	v_cvt_pk_bf16_f32 v10, v18, v19
	v_cvt_pk_bf16_f32 v11, v16, v17
	v_cvt_pk_bf16_f32 v2, v2, v3
	v_cvt_pk_bf16_f32 v3, v6, v7
	global_store_dwordx2 v[84:85], v[4:5], off offset:-64
	global_store_dwordx2 v[84:85], v[8:9], off offset:-32
	global_store_dwordx2 v[84:85], v[10:11], off
	global_store_dwordx2 v[84:85], v[2:3], off offset:32
	v_lshl_add_u64 v[84:85], v[84:85], 0, s[96:97]
	s_cbranch_scc1 .LBB0_600
; __device__ __forceinline__ u32x4 ld8_f32(const float* p) { const f32x4 a = *(const f32x4*)p, b = *(const f32x4*)(p + 4); u32x4 w; w.x = pk2(a[0], a[1]); w.y = pk2(a[2], a[3]); w.z = pk2(b[0], b[1]); w.w = pk2(b[2], b[3]); return w; }
; __device__ __forceinline__ void win_attn_sample_unit(int unit, const bf16* Z, const float* cK, const float* cV, bf16* HB, const float* sinks, LAS unsigned char* lds, int tid, int wave, int lane) {
;     ...
;     const int kvh = unit & 3, b = unit >> 2; const int fr = lane & 15, fq = lane >> 4;
; #pragma unroll
;     for (int idx = tid; idx < 160 * 8; idx += 512) { const int kl = idx >> 3, dc = idx & 7;
;         u32x4 kv = (u32x4){0u, 0u, 0u, 0u}, vv = kv;
;         if (kl < 128) { const size_t off = ((size_t)(b * 128 + kl) * 4 + kvh) * 64 + dc * 8; kv = ld8_f32(cK + off); vv = ld8_f32(cV + off); }
;         else if (kl < 136) { const bf16* zr = Z + (size_t)(MP + b * 8 + (kl - 128)) * NIN + kvh * 64 + dc * 8; kv = ld8_bf16(zr + ZKA); vv = ld8_bf16(zr + ZVA); }
;         put_k(Kl, KSTR, kl, dc, kv); put_vt(Vl, VSTR, kl, dc, vv); }
;     __syncthreads();
;     if (wave < 2) { const int g = wave * 2 + (fr >> 3), hq = kvh * 4 + g, ti = fr & 7; const float slope = exp2f(-0.5f * (float)(hq + 1)), sink = sinks[hq];
;         const size_t row = (size_t)MP + b * 8 + ti;
;         bf16x8 qf[2];
; #pragma unroll
;         for (int ks = 0; ks < 2; ++ks) qf[ks] = __builtin_bit_cast(bf16x8, ld8_bf16(Z + row * NIN + ZQA + hq * 64 + ks * 32 + fq * 8));
;         f32x4 o[4];
;         attn_group<64, 10, true>(Kl, KSTR, Vl, VSTR, qf, PAST + ti, PAST - 128, slope, sink, 0.125f, fr, fq, o);
; __global__ void __launch_bounds__(512, 2) mega_fwd(Params p) {
;     ...
;     for (int u = bx; u < 512; u += G) win_attn_prompt_unit(u, Z, HB, p.in[16], lds, tid, wave, lane);
;     for (int u = bx; u < 512; u += G) win_attn_sample_unit(u, Z, p.in[3], p.in[4], HB, p.in[16], lds, tid, wave, lane);
	s_add_i32 s76, s76, s94
	s_add_i32 s74, s74, s75
	s_add_i32 s2, s2, s94
	s_cmpk_gt_i32 s76, 0x1ff
	s_mov_b32 s96, s6
	v_readlane_b32 s71, v254, 61
	v_readlane_b32 s97, v255, 22
	s_barrier
	s_cbranch_scc0 .LBB0_592
	v_lshrrev_b32_e32 v2, 3, v217
	v_readlane_b32 s3, v254, 23
	v_or_b32_e32 v10, 0x4000, v75
	s_movk_i32 s2, 0x80
	v_lshl_or_b32 v101, s3, 1, v2
	v_sub_u32_e32 v2, v10, v72
	v_add_u32_e32 v3, 0xffffc080, v2
	v_cmp_gt_u32_e64 s[16:17], s2, v3
	v_cvt_f32_u32_e32 v13, v3
	v_add_u32_e32 v3, 0xffffc07f, v2
	v_cmp_gt_u32_e64 s[18:19], s2, v3
	v_cvt_f32_u32_e32 v15, v3
	v_add_u32_e32 v3, 0xffffc07e, v2
	v_cmp_gt_u32_e64 s[20:21], s2, v3
	v_cvt_f32_u32_e32 v17, v3
	v_add_u32_e32 v3, 0xffffc07d, v2
	v_cmp_gt_u32_e64 s[22:23], s2, v3
	v_cvt_f32_u32_e32 v19, v3
	v_add_u32_e32 v3, 0xffffc070, v2
	v_cvt_f32_u32_e32 v21, v3
	v_add_u32_e32 v3, 0xffffc06f, v2
	v_cvt_f32_u32_e32 v23, v3
	v_add_u32_e32 v3, 0xffffc06e, v2
	v_cvt_f32_u32_e32 v25, v3
	v_add_u32_e32 v3, 0xffffc06d, v2
	v_cvt_f32_u32_e32 v27, v3
	v_add_u32_e32 v3, 0xffffc060, v2
	v_cvt_f32_u32_e32 v29, v3
	v_add_u32_e32 v3, 0xffffc05f, v2
	v_cvt_f32_u32_e32 v31, v3
	v_add_u32_e32 v3, 0xffffc05e, v2
	v_cvt_f32_u32_e32 v33, v3
	v_add_u32_e32 v3, 0xffffc05d, v2
	v_cvt_f32_u32_e32 v35, v3
	v_add_u32_e32 v3, 0xffffc050, v2
	v_cvt_f32_u32_e32 v37, v3
	v_add_u32_e32 v3, 0xffffc04f, v2
	v_cvt_f32_u32_e32 v39, v3
	v_add_u32_e32 v3, 0xffffc04e, v2
	v_cvt_f32_u32_e32 v41, v3
	v_add_u32_e32 v3, 0xffffc04d, v2
	v_cvt_f32_u32_e32 v43, v3
	v_add_u32_e32 v3, 0xffffc040, v2
	v_cvt_f32_u32_e32 v45, v3
	v_add_u32_e32 v3, 0xffffc03f, v2
	v_cvt_f32_u32_e32 v47, v3
	v_add_u32_e32 v3, 0xffffc03e, v2
	v_cvt_f32_u32_e32 v49, v3
	v_add_u32_e32 v3, 0xffffc03d, v2
	v_cvt_f32_u32_e32 v51, v3
	v_add_u32_e32 v3, 0xffffc030, v2
	v_cvt_f32_u32_e32 v53, v3
	v_add_u32_e32 v3, 0xffffc02f, v2
	v_cvt_f32_u32_e32 v55, v3
	v_add_u32_e32 v3, 0xffffc02e, v2
	v_cvt_f32_u32_e32 v57, v3
	v_add_u32_e32 v3, 0xffffc02d, v2
	v_cvt_f32_u32_e32 v59, v3
	v_add_u32_e32 v3, 0xffffc020, v2
	v_cvt_f32_u32_e32 v61, v3
	v_add_u32_e32 v3, 0xffffc01f, v2
	v_cvt_f32_u32_e32 v63, v3
	v_add_u32_e32 v3, 0xffffc01e, v2
	v_cvt_f32_u32_e32 v65, v3
	v_add_u32_e32 v3, 0xffffc01d, v2
	v_cvt_f32_u32_e32 v75, v3
	v_add_u32_e32 v3, 0xffffc010, v2
	v_cvt_f32_u32_e32 v77, v3
	v_add_u32_e32 v3, 0xffffc00f, v2
	v_cvt_f32_u32_e32 v79, v3
	v_add_u32_e32 v3, 0xffffc00e, v2
	s_movk_i32 s0, 0x300
	v_cvt_f32_u32_e32 v81, v3
	v_add_u32_e32 v3, 0xffffc00d, v2
	v_cmp_gt_u32_e64 s[6:7], s0, v1
	s_movk_i32 s0, 0x1ff
	v_cvt_f32_u32_e32 v83, v3
	v_add_u32_e32 v3, 0xffffc000, v2
	v_cmp_lt_u32_e64 s[8:9], s0, v1
	s_movk_i32 s0, 0x240
	v_cmp_gt_u32_e64 s[24:25], s2, v3
	v_cvt_f32_i32_e32 v85, v3
	v_add_u32_e32 v3, 0xffffbfff, v2
	v_cmp_gt_u32_e64 s[10:11], s0, v1
	s_movk_i32 s0, 0x100
	v_cmp_gt_u32_e64 s[26:27], s2, v3
	v_cvt_f32_i32_e32 v87, v3
	v_add_u32_e32 v3, 0xffffbffe, v2
	v_add_u32_e32 v2, 0xffffbffd, v2
	v_cmp_gt_u32_e64 s[12:13], s0, v1
	s_movk_i32 s0, 0x440
	v_cvt_f32_i32_e32 v89, v3
	v_cvt_f32_i32_e32 v91, v2
	v_cmp_gt_u32_e64 s[14:15], s0, v88
	v_readlane_b32 s0, v254, 3
	v_readlane_b32 s76, v255, 42
	s_cmpk_lt_u32 s0, 0x80
	v_mov_b32_e32 v69, 0
	v_mov_b32_e32 v90, 0x3e000000
	v_readlane_b32 s77, v255, 43
	v_readlane_b32 s74, v255, 18
	s_cselect_b64 s[0:1], -1, 0
	v_mov_b32_e32 v11, v69
	v_cmp_gt_u32_e64 s[28:29], s2, v3
	v_cmp_gt_u32_e64 s[30:31], s2, v2
	v_mov_b32_e32 v88, v90
	v_mov_b32_e32 v86, v90
	v_mov_b32_e32 v84, v90
	v_mov_b32_e32 v82, v90
	v_mov_b32_e32 v80, v90
	v_mov_b32_e32 v78, v90
	v_mov_b32_e32 v76, v90
	v_mov_b32_e32 v74, v90
	v_mov_b32_e32 v64, v90
	v_mov_b32_e32 v62, v90
	v_mov_b32_e32 v60, v90
	v_mov_b32_e32 v58, v90
	v_mov_b32_e32 v56, v90
	v_mov_b32_e32 v54, v90
	v_mov_b32_e32 v52, v90
	v_mov_b32_e32 v50, v90
	v_mov_b32_e32 v48, v90
	v_mov_b32_e32 v46, v90
	v_mov_b32_e32 v44, v90
	v_mov_b32_e32 v42, v90
	v_mov_b32_e32 v40, v90
	v_mov_b32_e32 v38, v90
	v_mov_b32_e32 v36, v90
	v_mov_b32_e32 v34, v90
	v_mov_b32_e32 v32, v90
	v_mov_b32_e32 v30, v90
	v_mov_b32_e32 v28, v90
	v_mov_b32_e32 v26, v90
	v_mov_b32_e32 v24, v90
	v_mov_b32_e32 v22, v90
	v_mov_b32_e32 v20, v90
	v_mov_b32_e32 v18, v90
	v_mov_b32_e32 v16, v90
	v_mov_b32_e32 v14, v90
	v_mov_b32_e32 v12, v90
	s_movk_i32 s2, 0x2c00
	v_mov_b32_e32 v102, 0x42800000
	v_not_b32_e32 v103, 63
	v_mov_b32_e32 v104, 0xf149f2ca
	s_mov_b32 s3, s71
	v_readlane_b32 s75, v255, 19
	v_readlane_b32 s77, v255, 23
	s_branch .LBB0_604

; template <int XSRC, bool HAS_F, bool HAS_NEXT, bool SPLIT, int XDST  > ...
;     ...
;             if (SPLIT && row >= MP) {
; #pragma unroll
;                 for (int i = 0; i < 8; ++i) { const float* pr = part + (size_t)(row - MP) * DM + (i >> 1) * 512 + lane * 8 + (i & 1) * 4; f32x4 a = *(const f32x4*)pr;
; #pragma unroll
;                     for (int s = 1; s < 8; ++s) a = a + *(const f32x4*)(pr + (size_t)s * 1024 * DM);
;                     f[i] = a; __builtin_amdgcn_sched_barrier(0); } }
.LBB0_1609:
	s_add_i32 s0, s76, 0xffffc000
	s_lshl_b64 s[10:11], s[0:1], 13
	v_lshl_add_u64 v[82:83], v[102:103], 0, s[10:11]
	s_mov_b32 s10, 0x800000
	s_mov_b32 s11, 0
	v_lshl_add_u64 v[84:85], v[82:83], 0, s[10:11]
	v_lshl_add_u64 v[86:87], v[84:85], 0, s[10:11]
	v_lshl_add_u64 v[88:89], v[86:87], 0, s[10:11]
	v_lshl_add_u64 v[90:91], v[88:89], 0, s[10:11]
	v_lshl_add_u64 v[92:93], v[90:91], 0, s[10:11]
	v_lshl_add_u64 v[98:99], v[92:93], 0, s[10:11]
	v_lshl_add_u64 v[100:101], v[98:99], 0, s[10:11]
	global_load_dwordx4 v[22:25], v[82:83], off
	global_load_dwordx4 v[26:29], v[84:85], off
	global_load_dwordx4 v[30:33], v[86:87], off
	global_load_dwordx4 v[34:37], v[88:89], off
	global_load_dwordx4 v[38:41], v[90:91], off
	global_load_dwordx4 v[42:45], v[92:93], off
	global_load_dwordx4 v[46:49], v[98:99], off
	global_load_dwordx4 v[50:53], v[100:101], off
	s_waitcnt vmcnt(6)
	v_pk_add_f32 v[56:57], v[24:25], v[28:29]
	v_pk_add_f32 v[54:55], v[22:23], v[26:27]
	s_waitcnt vmcnt(5)
	v_pk_add_f32 v[56:57], v[56:57], v[32:33]
	v_pk_add_f32 v[54:55], v[54:55], v[30:31]
	s_waitcnt vmcnt(4)
	v_pk_add_f32 v[56:57], v[56:57], v[36:37]
	v_pk_add_f32 v[54:55], v[54:55], v[34:35]
	s_waitcnt vmcnt(3)
	v_pk_add_f32 v[56:57], v[56:57], v[40:41]
	v_pk_add_f32 v[54:55], v[54:55], v[38:39]
	s_waitcnt vmcnt(2)
	v_pk_add_f32 v[56:57], v[56:57], v[44:45]
	v_pk_add_f32 v[54:55], v[54:55], v[42:43]
	s_waitcnt vmcnt(1)
	v_pk_add_f32 v[56:57], v[56:57], v[48:49]
	v_pk_add_f32 v[54:55], v[54:55], v[46:47]
	s_waitcnt vmcnt(0)
	v_pk_add_f32 v[56:57], v[56:57], v[52:53]
	v_pk_add_f32 v[54:55], v[54:55], v[50:51]
	global_load_dwordx4 v[22:25], v[82:83], off offset:16
	global_load_dwordx4 v[26:29], v[84:85], off offset:16
	global_load_dwordx4 v[30:33], v[86:87], off offset:16
	global_load_dwordx4 v[34:37], v[88:89], off offset:16
	global_load_dwordx4 v[38:41], v[90:91], off offset:16
	global_load_dwordx4 v[42:45], v[92:93], off offset:16
	global_load_dwordx4 v[46:49], v[98:99], off offset:16
	global_load_dwordx4 v[50:53], v[100:101], off offset:16
	s_waitcnt vmcnt(6)
	v_pk_add_f32 v[60:61], v[24:25], v[28:29]
	v_pk_add_f32 v[58:59], v[22:23], v[26:27]
	s_waitcnt vmcnt(5)
	v_pk_add_f32 v[60:61], v[60:61], v[32:33]
	v_pk_add_f32 v[58:59], v[58:59], v[30:31]
	s_waitcnt vmcnt(4)
	v_pk_add_f32 v[60:61], v[60:61], v[36:37]
	v_pk_add_f32 v[58:59], v[58:59], v[34:35]
	s_waitcnt vmcnt(3)
	v_pk_add_f32 v[60:61], v[60:61], v[40:41]
	v_pk_add_f32 v[58:59], v[58:59], v[38:39]
	s_waitcnt vmcnt(2)
	v_pk_add_f32 v[60:61], v[60:61], v[44:45]
	v_pk_add_f32 v[58:59], v[58:59], v[42:43]
	s_waitcnt vmcnt(1)
	v_pk_add_f32 v[60:61], v[60:61], v[48:49]
	v_pk_add_f32 v[58:59], v[58:59], v[46:47]
	s_waitcnt vmcnt(0)
	v_pk_add_f32 v[60:61], v[60:61], v[52:53]
	v_pk_add_f32 v[58:59], v[58:59], v[50:51]
	global_load_dwordx4 v[22:25], v[82:83], off offset:2048
	global_load_dwordx4 v[26:29], v[84:85], off offset:2048
	global_load_dwordx4 v[30:33], v[86:87], off offset:2048
	global_load_dwordx4 v[34:37], v[88:89], off offset:2048
	global_load_dwordx4 v[38:41], v[90:91], off offset:2048
	global_load_dwordx4 v[42:45], v[92:93], off offset:2048
	global_load_dwordx4 v[46:49], v[98:99], off offset:2048
	global_load_dwordx4 v[50:53], v[100:101], off offset:2048
	s_waitcnt vmcnt(6)
	v_pk_add_f32 v[64:65], v[24:25], v[28:29]
	v_pk_add_f32 v[62:63], v[22:23], v[26:27]
	s_waitcnt vmcnt(5)
	v_pk_add_f32 v[64:65], v[64:65], v[32:33]
	v_pk_add_f32 v[62:63], v[62:63], v[30:31]
	s_waitcnt vmcnt(4)
	v_pk_add_f32 v[64:65], v[64:65], v[36:37]
	v_pk_add_f32 v[62:63], v[62:63], v[34:35]
	s_waitcnt vmcnt(3)
	v_pk_add_f32 v[64:65], v[64:65], v[40:41]
	v_pk_add_f32 v[62:63], v[62:63], v[38:39]
	s_waitcnt vmcnt(2)
	v_pk_add_f32 v[64:65], v[64:65], v[44:45]
	v_pk_add_f32 v[62:63], v[62:63], v[42:43]
	s_waitcnt vmcnt(1)
	v_pk_add_f32 v[64:65], v[64:65], v[48:49]
	v_pk_add_f32 v[62:63], v[62:63], v[46:47]
	s_waitcnt vmcnt(0)
	v_pk_add_f32 v[64:65], v[64:65], v[52:53]
	v_pk_add_f32 v[62:63], v[62:63], v[50:51]
	global_load_dwordx4 v[22:25], v[82:83], off offset:2064
	global_load_dwordx4 v[26:29], v[84:85], off offset:2064
	global_load_dwordx4 v[30:33], v[86:87], off offset:2064
	global_load_dwordx4 v[34:37], v[88:89], off offset:2064
	global_load_dwordx4 v[38:41], v[90:91], off offset:2064
	global_load_dwordx4 v[42:45], v[92:93], off offset:2064
	global_load_dwordx4 v[46:49], v[98:99], off offset:2064
	global_load_dwordx4 v[50:53], v[100:101], off offset:2064
	s_waitcnt vmcnt(6)
	v_pk_add_f32 v[68:69], v[24:25], v[28:29]
	v_pk_add_f32 v[66:67], v[22:23], v[26:27]
	s_waitcnt vmcnt(5)
	v_pk_add_f32 v[68:69], v[68:69], v[32:33]
	v_pk_add_f32 v[66:67], v[66:67], v[30:31]
	s_waitcnt vmcnt(4)
	v_pk_add_f32 v[68:69], v[68:69], v[36:37]
	v_pk_add_f32 v[66:67], v[66:67], v[34:35]
	s_waitcnt vmcnt(3)
	v_pk_add_f32 v[68:69], v[68:69], v[40:41]
	v_pk_add_f32 v[66:67], v[66:67], v[38:39]
	s_waitcnt vmcnt(2)
	v_pk_add_f32 v[68:69], v[68:69], v[44:45]
	v_pk_add_f32 v[66:67], v[66:67], v[42:43]
	s_waitcnt vmcnt(1)
	v_pk_add_f32 v[68:69], v[68:69], v[48:49]
	v_pk_add_f32 v[66:67], v[66:67], v[46:47]
	s_waitcnt vmcnt(0)
; template <int XSRC, bool HAS_F, bool HAS_NEXT, bool SPLIT, int XDST  > ...
;     ...
;             if (SPLIT && row >= MP) {
; #pragma unroll
;                 for (int i = 0; i < 8; ++i) { const float* pr = part + (size_t)(row - MP) * DM + (i >> 1) * 512 + lane * 8 + (i & 1) * 4; f32x4 a = *(const f32x4*)pr;
; #pragma unroll
;                     for (int s = 1; s < 8; ++s) a = a + *(const f32x4*)(pr + (size_t)s * 1024 * DM);
;                     f[i] = a; __builtin_amdgcn_sched_barrier(0); } }
	v_pk_add_f32 v[68:69], v[68:69], v[52:53]
	v_pk_add_f32 v[66:67], v[66:67], v[50:51]
	s_movk_i32 s10, 0x1000
	v_lshl_add_u64 v[82:83], v[82:83], 0, s[10:11]
	v_lshl_add_u64 v[84:85], v[84:85], 0, s[10:11]
	v_lshl_add_u64 v[86:87], v[86:87], 0, s[10:11]
	v_lshl_add_u64 v[88:89], v[88:89], 0, s[10:11]
	v_lshl_add_u64 v[90:91], v[90:91], 0, s[10:11]
	v_lshl_add_u64 v[92:93], v[92:93], 0, s[10:11]
	v_lshl_add_u64 v[98:99], v[98:99], 0, s[10:11]
	v_lshl_add_u64 v[100:101], v[100:101], 0, s[10:11]
	global_load_dwordx4 v[22:25], v[82:83], off
	global_load_dwordx4 v[26:29], v[84:85], off
	global_load_dwordx4 v[30:33], v[86:87], off
	global_load_dwordx4 v[34:37], v[88:89], off
	global_load_dwordx4 v[38:41], v[90:91], off
	global_load_dwordx4 v[42:45], v[92:93], off
	global_load_dwordx4 v[46:49], v[98:99], off
	global_load_dwordx4 v[50:53], v[100:101], off
	s_waitcnt vmcnt(6)
	v_pk_add_f32 v[72:73], v[24:25], v[28:29]
	v_pk_add_f32 v[70:71], v[22:23], v[26:27]
	s_waitcnt vmcnt(5)
	v_pk_add_f32 v[72:73], v[72:73], v[32:33]
	v_pk_add_f32 v[70:71], v[70:71], v[30:31]
	s_waitcnt vmcnt(4)
	v_pk_add_f32 v[72:73], v[72:73], v[36:37]
	v_pk_add_f32 v[70:71], v[70:71], v[34:35]
	s_waitcnt vmcnt(3)
	v_pk_add_f32 v[72:73], v[72:73], v[40:41]
	v_pk_add_f32 v[70:71], v[70:71], v[38:39]
	s_waitcnt vmcnt(2)
	v_pk_add_f32 v[72:73], v[72:73], v[44:45]
	v_pk_add_f32 v[70:71], v[70:71], v[42:43]
	s_waitcnt vmcnt(1)
	v_pk_add_f32 v[72:73], v[72:73], v[48:49]
	v_pk_add_f32 v[70:71], v[70:71], v[46:47]
	s_waitcnt vmcnt(0)
	v_pk_add_f32 v[72:73], v[72:73], v[52:53]
	v_pk_add_f32 v[70:71], v[70:71], v[50:51]
	global_load_dwordx4 v[22:25], v[82:83], off offset:16
	global_load_dwordx4 v[26:29], v[84:85], off offset:16
	global_load_dwordx4 v[30:33], v[86:87], off offset:16
	global_load_dwordx4 v[34:37], v[88:89], off offset:16
	global_load_dwordx4 v[38:41], v[90:91], off offset:16
	global_load_dwordx4 v[42:45], v[92:93], off offset:16
	global_load_dwordx4 v[46:49], v[98:99], off offset:16
	global_load_dwordx4 v[50:53], v[100:101], off offset:16
	s_waitcnt vmcnt(6)
	v_pk_add_f32 v[76:77], v[24:25], v[28:29]
	v_pk_add_f32 v[74:75], v[22:23], v[26:27]
	s_waitcnt vmcnt(5)
	v_pk_add_f32 v[76:77], v[76:77], v[32:33]
	v_pk_add_f32 v[74:75], v[74:75], v[30:31]
	s_waitcnt vmcnt(4)
	v_pk_add_f32 v[76:77], v[76:77], v[36:37]
	v_pk_add_f32 v[74:75], v[74:75], v[34:35]
	s_waitcnt vmcnt(3)
	v_pk_add_f32 v[76:77], v[76:77], v[40:41]
	v_pk_add_f32 v[74:75], v[74:75], v[38:39]
	s_waitcnt vmcnt(2)
	v_pk_add_f32 v[76:77], v[76:77], v[44:45]
	v_pk_add_f32 v[74:75], v[74:75], v[42:43]
	s_waitcnt vmcnt(1)
	v_pk_add_f32 v[76:77], v[76:77], v[48:49]
	v_pk_add_f32 v[74:75], v[74:75], v[46:47]
	s_waitcnt vmcnt(0)
	v_pk_add_f32 v[76:77], v[76:77], v[52:53]
	v_pk_add_f32 v[74:75], v[74:75], v[50:51]
	global_load_dwordx4 v[22:25], v[82:83], off offset:2048
	global_load_dwordx4 v[26:29], v[84:85], off offset:2048
	global_load_dwordx4 v[30:33], v[86:87], off offset:2048
	global_load_dwordx4 v[34:37], v[88:89], off offset:2048
	global_load_dwordx4 v[38:41], v[90:91], off offset:2048
	global_load_dwordx4 v[42:45], v[92:93], off offset:2048
	global_load_dwordx4 v[46:49], v[98:99], off offset:2048
	global_load_dwordx4 v[50:53], v[100:101], off offset:2048
	s_waitcnt vmcnt(6)
	v_pk_add_f32 v[80:81], v[24:25], v[28:29]
	v_pk_add_f32 v[78:79], v[22:23], v[26:27]
	s_waitcnt vmcnt(5)
	v_pk_add_f32 v[80:81], v[80:81], v[32:33]
	v_pk_add_f32 v[78:79], v[78:79], v[30:31]
	s_waitcnt vmcnt(4)
	v_pk_add_f32 v[80:81], v[80:81], v[36:37]
	v_pk_add_f32 v[78:79], v[78:79], v[34:35]
	s_waitcnt vmcnt(3)
	v_pk_add_f32 v[80:81], v[80:81], v[40:41]
	v_pk_add_f32 v[78:79], v[78:79], v[38:39]
	s_waitcnt vmcnt(2)
	v_pk_add_f32 v[80:81], v[80:81], v[44:45]
	v_pk_add_f32 v[78:79], v[78:79], v[42:43]
	s_waitcnt vmcnt(1)
	v_pk_add_f32 v[80:81], v[80:81], v[48:49]
	v_pk_add_f32 v[78:79], v[78:79], v[46:47]
	s_waitcnt vmcnt(0)
	v_pk_add_f32 v[80:81], v[80:81], v[52:53]
	v_pk_add_f32 v[78:79], v[78:79], v[50:51]
	global_load_dwordx4 v[22:25], v[82:83], off offset:2064
	global_load_dwordx4 v[26:29], v[84:85], off offset:2064
	global_load_dwordx4 v[30:33], v[86:87], off offset:2064
	global_load_dwordx4 v[34:37], v[88:89], off offset:2064
	global_load_dwordx4 v[38:41], v[90:91], off offset:2064
	global_load_dwordx4 v[42:45], v[92:93], off offset:2064
	global_load_dwordx4 v[46:49], v[98:99], off offset:2064
	global_load_dwordx4 v[50:53], v[100:101], off offset:2064
	s_waitcnt vmcnt(6)
	v_pk_add_f32 v[96:97], v[24:25], v[28:29]
	v_pk_add_f32 v[94:95], v[22:23], v[26:27]
	s_waitcnt vmcnt(5)
	v_pk_add_f32 v[96:97], v[96:97], v[32:33]
	v_pk_add_f32 v[94:95], v[94:95], v[30:31]
	s_waitcnt vmcnt(4)
	v_pk_add_f32 v[96:97], v[96:97], v[36:37]
	v_pk_add_f32 v[94:95], v[94:95], v[34:35]
	s_waitcnt vmcnt(3)
	v_pk_add_f32 v[96:97], v[96:97], v[40:41]
	v_pk_add_f32 v[94:95], v[94:95], v[38:39]
	s_waitcnt vmcnt(2)
	v_pk_add_f32 v[96:97], v[96:97], v[44:45]
	v_pk_add_f32 v[94:95], v[94:95], v[42:43]
	s_waitcnt vmcnt(1)
	v_pk_add_f32 v[96:97], v[96:97], v[48:49]
	v_pk_add_f32 v[94:95], v[94:95], v[46:47]
	s_waitcnt vmcnt(0)
	v_pk_add_f32 v[96:97], v[96:97], v[52:53]
	v_pk_add_f32 v[94:95], v[94:95], v[50:51]
	v_mov_b64_e32 v[22:23], 0
	v_mov_b64_e32 v[24:25], 0
	v_mov_b64_e32 v[26:27], 0
	v_mov_b64_e32 v[28:29], 0
	v_mov_b64_e32 v[30:31], 0
	v_mov_b64_e32 v[32:33], 0
	v_mov_b64_e32 v[34:35], 0
	v_mov_b64_e32 v[36:37], 0
	v_mov_b64_e32 v[38:39], 0
	v_mov_b64_e32 v[40:41], 0
	v_mov_b64_e32 v[42:43], 0
	v_mov_b64_e32 v[44:45], 0
	v_mov_b64_e32 v[46:47], 0
	v_mov_b64_e32 v[48:49], 0
	v_mov_b64_e32 v[50:51], 0
	v_mov_b64_e32 v[52:53], 0
	s_branch .LBB0_1601
